# v27 + rotated k-loops (barrier ahead of the previous slice's last MFMA group, DMA interleaved) for M2/E2/E4/O5
# baseline (speedup 1.0000x reference)
.LBB0_680:
	s_waitcnt vmcnt(0)
	ds_write_b32 v2, v246
	v_ashrrev_i32_e32 v103, 6, v100
	v_lshrrev_b32_e32 v0, 30, v103
	v_add_u32_e32 v0, v103, v0
	v_ashrrev_i32_e32 v10, 2, v0
	v_mul_i32_i24_e32 v0, 4, v10
	v_ashrrev_i32_e32 v6, 3, v100
	v_sub_u32_e32 v11, v103, v0
	v_lshrrev_b32_e32 v13, 4, v100
	v_add_u32_e32 v0, s4, v6
	v_xor_b32_e32 v7, v13, v100
	v_ashrrev_i32_e32 v1, 31, v0
	v_lshlrev_b64 v[0:1], 11, v[0:1]
	v_lshlrev_b32_e32 v7, 4, v7
	v_lshlrev_b32_e32 v109, 4, v100
	s_and_b32 s8, s2, 0xffffff00
	v_lshl_add_u64 v[4:5], s[50:51], 0, v[0:1]
	v_and_b32_e32 v128, 0x70, v7
	v_readfirstlane_b32 s2, v109
	v_add_u32_e32 v14, 0x2000, v109
	v_lshl_add_u64 v[4:5], v[4:5], 0, v[128:129]
	s_mov_b32 m0, s2
	s_mov_b64 s[10:11], 0x20000
	v_readfirstlane_b32 s2, v14
	ds_write_b32 v2, v3 offset:2048
	v_lshl_add_u64 v[2:3], v[4:5], 0, s[10:11]
	s_mov_b32 m0, s2
	s_mov_b64 s[12:13], 0x40000
	v_lshl_add_u64 v[2:3], v[4:5], 0, s[12:13]
	v_add_u32_e32 v4, 0x4000, v109
	v_add_u32_e32 v6, s8, v6
	v_readfirstlane_b32 s2, v4
	v_ashrrev_i32_e32 v7, 31, v6
	s_mov_b32 m0, s2
	v_lshlrev_b64 v[6:7], 11, v[6:7]
	v_add_u32_e32 v2, 0x6000, v109
	v_lshl_add_u64 v[8:9], s[60:61], 0, v[6:7]
	v_readfirstlane_b32 s2, v2
	v_add_u32_e32 v4, 0x8000, v109
	v_lshl_add_u64 v[8:9], v[8:9], 0, v[128:129]
	s_mov_b32 m0, s2
	v_readfirstlane_b32 s2, v4
	v_add_u32_e32 v4, 0xa000, v109
	v_lshl_add_u64 v[2:3], v[8:9], 0, s[10:11]
	s_mov_b32 m0, s2
	v_readfirstlane_b32 s2, v4
	v_lshl_add_u64 v[2:3], v[8:9], 0, s[12:13]
	s_mov_b32 m0, s2
	s_mov_b64 s[2:3], 0x60000
	v_add_u32_e32 v4, 0xc000, v109
	v_lshl_add_u64 v[2:3], v[8:9], 0, s[2:3]
	v_readfirstlane_b32 s2, v4
	s_mov_b32 m0, s2
	v_and_b32_e32 v102, 31, v100
	v_lshlrev_b32_e32 v105, 6, v11
	v_or_b32_e32 v3, v105, v102
	v_mul_i32_i24_e32 v106, 0x60, v10
	v_bfe_u32 v12, v100, 5, 1
	v_lshrrev_b32_e32 v104, 1, v100
	v_lshlrev_b32_e32 v112, 7, v3
	v_or_b32_e32 v3, v106, v102
	v_bfe_u32 v2, v100, 1, 3
	v_lshlrev_b32_e32 v113, 7, v3
	v_bitop3_b32 v3, v12, v104, 7 bitop3:0x78
	v_lshlrev_b32_e32 v111, 4, v3
	v_bitop3_b32 v3, v12, v2, 2 bitop3:0x36
	v_lshlrev_b32_e32 v110, 4, v3
	v_bitop3_b32 v3, v12, v2, 4 bitop3:0x36
	v_bitop3_b32 v2, v12, v2, 6 bitop3:0x36
	v_lshlrev_b32_e32 v107, 4, v2
	v_bitop3_b32 v2, v13, 7, v100 bitop3:0x48
	v_lshlrev_b32_e32 v2, 4, v2
	v_or_b32_e32 v6, v6, v2
	v_or_b32_e32 v0, v0, v2
	v_and_b32_e32 v101, 63, v100
	v_lshlrev_b32_e32 v108, 4, v3
	v_add_u32_e32 v114, 0x6000, v112
	v_lshl_add_u64 v[96:97], s[62:63], 0, v[6:7]
	v_lshl_add_u64 v[98:99], s[14:15], 0, v[0:1]
	s_mov_b32 s7, 0
	s_mov_b64 s[2:3], 0
	v_mov_b32_e32 v33, v32
	v_mov_b32_e32 v34, v32
	v_mov_b32_e32 v35, v32
	v_mov_b32_e32 v36, v32
	v_mov_b32_e32 v37, v32
	v_mov_b32_e32 v38, v32
	v_mov_b32_e32 v39, v32
	v_mov_b32_e32 v40, v32
	v_mov_b32_e32 v41, v32
	v_mov_b32_e32 v42, v32
	v_mov_b32_e32 v43, v32
	v_mov_b32_e32 v44, v32
	v_mov_b32_e32 v45, v32
	v_mov_b32_e32 v46, v32
	v_mov_b32_e32 v47, v32
	v_mov_b32_e32 v64, v32
	v_mov_b32_e32 v65, v32
	v_mov_b32_e32 v66, v32
	v_mov_b32_e32 v67, v32
	v_mov_b32_e32 v68, v32
	v_mov_b32_e32 v69, v32
	v_mov_b32_e32 v70, v32
	v_mov_b32_e32 v71, v32
	v_mov_b32_e32 v72, v32
	v_mov_b32_e32 v73, v32
	v_mov_b32_e32 v74, v32
	v_mov_b32_e32 v75, v32
	v_mov_b32_e32 v76, v32
	v_mov_b32_e32 v77, v32
	v_mov_b32_e32 v78, v32
	v_mov_b32_e32 v79, v32
	v_mov_b32_e32 v0, v32
	v_mov_b32_e32 v1, v32
	v_mov_b32_e32 v2, v32
	v_mov_b32_e32 v3, v32
	v_mov_b32_e32 v4, v32
	v_mov_b32_e32 v5, v32
	v_mov_b32_e32 v6, v32
	v_mov_b32_e32 v7, v32
	v_mov_b32_e32 v8, v32
	v_mov_b32_e32 v9, v32
	v_mov_b32_e32 v10, v32
	v_mov_b32_e32 v11, v32
	v_mov_b32_e32 v12, v32
	v_mov_b32_e32 v13, v32
	v_mov_b32_e32 v14, v32
	v_mov_b32_e32 v15, v32
	v_mov_b32_e32 v80, v32
	v_mov_b32_e32 v81, v32
	v_mov_b32_e32 v82, v32
	v_mov_b32_e32 v83, v32
	v_mov_b32_e32 v84, v32
	v_mov_b32_e32 v85, v32
	v_mov_b32_e32 v86, v32
	v_mov_b32_e32 v87, v32
	v_mov_b32_e32 v88, v32
	v_mov_b32_e32 v89, v32
	v_mov_b32_e32 v90, v32
	v_mov_b32_e32 v91, v32
	v_mov_b32_e32 v92, v32
	v_mov_b32_e32 v93, v32
	v_mov_b32_e32 v94, v32
	v_mov_b32_e32 v95, v32
	v_mov_b32_e32 v48, v32
	v_mov_b32_e32 v49, v32
	v_mov_b32_e32 v50, v32
	v_mov_b32_e32 v51, v32
	v_mov_b32_e32 v52, v32
	v_mov_b32_e32 v53, v32
	v_mov_b32_e32 v54, v32
	v_mov_b32_e32 v55, v32
	v_mov_b32_e32 v56, v32
	v_mov_b32_e32 v57, v32
	v_mov_b32_e32 v58, v32
	v_mov_b32_e32 v59, v32
	v_mov_b32_e32 v60, v32
	v_mov_b32_e32 v61, v32
	v_mov_b32_e32 v62, v32
	v_mov_b32_e32 v63, v32
	v_mov_b32_e32 v16, v32
	v_mov_b32_e32 v17, v32
	v_mov_b32_e32 v18, v32
	v_mov_b32_e32 v19, v32
	v_mov_b32_e32 v20, v32
	v_mov_b32_e32 v21, v32
	v_mov_b32_e32 v22, v32
	v_mov_b32_e32 v23, v32
	v_mov_b32_e32 v24, v32
	v_mov_b32_e32 v25, v32
	v_mov_b32_e32 v26, v32
	v_mov_b32_e32 v27, v32
	v_mov_b32_e32 v28, v32
	v_mov_b32_e32 v29, v32
	v_mov_b32_e32 v30, v32
	v_mov_b32_e32 v31, v32
	s_mov_b64 s[12:13], 0x8794080
	s_mov_b64 s[16:17], 0x87b4080
	s_mov_b64 s[18:19], 0x87d4080
	v_add_u32_e32 v243, s4, v106
	v_lshrrev_b32_e32 v244, 4, v101
	v_or_b32_e32 v243, v243, v244
	v_and_b32_e32 v244, 15, v100
	v_add_u32_e32 v245, s8, v105
	v_lshl_or_b32 v244, v244, 2, v245
	v_lshlrev_b32_e32 v243, 12, v243
	v_lshl_add_u32 v243, v244, 2, v243
	global_load_dwordx4 v[198:201], v243, s[40:41]
	v_add_u32_e32 v243, 0x4000, v243
	global_load_dwordx4 v[202:205], v243, s[40:41]
	v_add_u32_e32 v243, 0x4000, v243
	global_load_dwordx4 v[206:209], v243, s[40:41]
	v_add_u32_e32 v243, 0x4000, v243
	global_load_dwordx4 v[210:213], v243, s[40:41]
	v_add_u32_e32 v243, 0x4000, v243
	global_load_dwordx4 v[214:217], v243, s[40:41]
	v_add_u32_e32 v243, 0x4000, v243
	global_load_dwordx4 v[218:221], v243, s[40:41]
	v_add_u32_e32 v243, 0x4000, v243
	global_load_dwordx4 v[222:225], v243, s[40:41]
	v_add_u32_e32 v243, 0x4000, v243
	global_load_dwordx4 v[226:229], v243, s[40:41]
	s_add_i32 s9, s7, 1
	s_bitcmp1_b32 s9, 0
	s_cselect_b32 s10, 0xe000, 0
	v_add_u32_e32 v246, s10, v109
	s_bitcmp1_b32 s7, 0
	s_cselect_b32 s10, 0xe000, 0
	v_add_u32_e32 v153, s10, v114
	v_add_u32_e32 v154, s10, v113
	s_waitcnt vmcnt(0) lgkmcnt(0)
	s_barrier
	v_add_u32_e32 v181, v153, v111
	ds_read_b128 v[116:119], v181 offset:0x0
	ds_read_b128 v[120:123], v181 offset:0x1000
	v_add_u32_e32 v181, v154, v111
	ds_read_b128 v[124:127], v181 offset:0x0
	ds_read_b128 v[130:133], v181 offset:0x1000
	ds_read_b128 v[134:137], v181 offset:0x2000
	v_add_u32_e32 v181, v153, v110
	ds_read_b128 v[144:147], v181 offset:0x0
	ds_read_b128 v[148:151], v181 offset:0x1000
	v_add_u32_e32 v181, v154, v110
	ds_read_b128 v[182:185], v181 offset:0x0
	ds_read_b128 v[186:189], v181 offset:0x1000
	ds_read_b128 v[190:193], v181 offset:0x2000
	s_waitcnt lgkmcnt(5)
	v_mfma_f32_32x32x16_bf16 v[64:79], v[116:119], v[124:127], v[64:79]
	v_mfma_f32_32x32x16_bf16 v[32:47], v[116:119], v[130:133], v[32:47]
	v_lshl_add_u64 v[244:245], v[98:99], 0, s[2:3]
	v_lshl_add_u64 v[244:245], v[244:245], 0, s[12:13]
	v_readfirstlane_b32 s10, v246
	s_mov_b32 m0, s10
	s_nop 0
	global_load_lds_dwordx4 v[244:245], off
	v_mfma_f32_32x32x16_bf16 v[0:15], v[116:119], v[134:137], v[0:15]
	v_mfma_f32_32x32x16_bf16 v[80:95], v[120:123], v[124:127], v[80:95]
	v_add_u32_e32 v243, 0x2000, v246
	v_lshl_add_u64 v[244:245], v[98:99], 0, s[2:3]
	v_lshl_add_u64 v[244:245], v[244:245], 0, s[16:17]
	v_readfirstlane_b32 s10, v243
	s_mov_b32 m0, s10
	s_nop 0
	global_load_lds_dwordx4 v[244:245], off
	v_mfma_f32_32x32x16_bf16 v[48:63], v[120:123], v[130:133], v[48:63]
	v_mfma_f32_32x32x16_bf16 v[16:31], v[120:123], v[134:137], v[16:31]
	v_add_u32_e32 v243, 0x4000, v246
	v_lshl_add_u64 v[244:245], v[98:99], 0, s[2:3]
	v_lshl_add_u64 v[244:245], v[244:245], 0, s[18:19]
	v_readfirstlane_b32 s10, v243
	s_mov_b32 m0, s10
	s_nop 0
	global_load_lds_dwordx4 v[244:245], off
	v_add_u32_e32 v181, v153, v108
	ds_read_b128 v[116:119], v181 offset:0x0
	ds_read_b128 v[120:123], v181 offset:0x1000
	v_add_u32_e32 v181, v154, v108
	ds_read_b128 v[124:127], v181 offset:0x0
	ds_read_b128 v[130:133], v181 offset:0x1000
	ds_read_b128 v[134:137], v181 offset:0x2000
	s_waitcnt lgkmcnt(5)
	v_mfma_f32_32x32x16_bf16 v[64:79], v[144:147], v[182:185], v[64:79]
	v_mfma_f32_32x32x16_bf16 v[32:47], v[144:147], v[186:189], v[32:47]
	v_add_u32_e32 v243, 0x6000, v246
	s_mov_b64 s[10:11], 0x6a94080
	v_lshl_add_u64 v[244:245], v[96:97], 0, s[2:3]
	v_lshl_add_u64 v[244:245], v[244:245], 0, s[10:11]
	v_readfirstlane_b32 s10, v243
	s_mov_b32 m0, s10
	s_nop 0
	global_load_lds_dwordx4 v[244:245], off
	v_mfma_f32_32x32x16_bf16 v[0:15], v[144:147], v[190:193], v[0:15]
	v_mfma_f32_32x32x16_bf16 v[80:95], v[148:151], v[182:185], v[80:95]
	v_add_u32_e32 v243, 0x8000, v246
	s_mov_b64 s[10:11], 0x6ab4080
	v_lshl_add_u64 v[244:245], v[96:97], 0, s[2:3]
	v_lshl_add_u64 v[244:245], v[244:245], 0, s[10:11]
	v_readfirstlane_b32 s10, v243
	s_mov_b32 m0, s10
	s_nop 0
	global_load_lds_dwordx4 v[244:245], off
	v_mfma_f32_32x32x16_bf16 v[48:63], v[148:151], v[186:189], v[48:63]
	v_mfma_f32_32x32x16_bf16 v[16:31], v[148:151], v[190:193], v[16:31]
	v_add_u32_e32 v243, 0xa000, v246
	s_mov_b64 s[10:11], 0x6ad4080
	v_lshl_add_u64 v[244:245], v[96:97], 0, s[2:3]
	v_lshl_add_u64 v[244:245], v[244:245], 0, s[10:11]
	v_readfirstlane_b32 s10, v243
	s_mov_b32 m0, s10
	s_nop 0
	global_load_lds_dwordx4 v[244:245], off
	v_add_u32_e32 v181, v153, v107
	ds_read_b128 v[144:147], v181 offset:0x0
	ds_read_b128 v[148:151], v181 offset:0x1000
	v_add_u32_e32 v181, v154, v107
	ds_read_b128 v[182:185], v181 offset:0x0
	ds_read_b128 v[186:189], v181 offset:0x1000
	ds_read_b128 v[190:193], v181 offset:0x2000
	s_waitcnt lgkmcnt(5)
	v_mfma_f32_32x32x16_bf16 v[64:79], v[116:119], v[124:127], v[64:79]
	v_mfma_f32_32x32x16_bf16 v[32:47], v[116:119], v[130:133], v[32:47]
	v_add_u32_e32 v243, 0xc000, v246
	s_mov_b64 s[10:11], 0x6af4080
	v_lshl_add_u64 v[244:245], v[96:97], 0, s[2:3]
	v_lshl_add_u64 v[244:245], v[244:245], 0, s[10:11]
	v_readfirstlane_b32 s10, v243
	s_mov_b32 m0, s10
	s_nop 0
	global_load_lds_dwordx4 v[244:245], off
	v_mfma_f32_32x32x16_bf16 v[0:15], v[116:119], v[134:137], v[0:15]
	v_mfma_f32_32x32x16_bf16 v[80:95], v[120:123], v[124:127], v[80:95]
	v_mfma_f32_32x32x16_bf16 v[48:63], v[120:123], v[130:133], v[48:63]
	v_mfma_f32_32x32x16_bf16 v[16:31], v[120:123], v[134:137], v[16:31]
	s_waitcnt lgkmcnt(0)
	s_add_u32 s2, s2, 0x80
	s_addc_u32 s3, s3, 0
	s_mov_b32 s7, s9
.LBB0_681:
	s_add_i32 s9, s7, 1
	s_bitcmp1_b32 s9, 0
	s_cselect_b32 s10, 0xe000, 0
	v_add_u32_e32 v246, s10, v109
	s_bitcmp1_b32 s7, 0
	s_cselect_b32 s10, 0xe000, 0
	v_add_u32_e32 v153, s10, v114
	v_add_u32_e32 v154, s10, v113
	s_waitcnt vmcnt(0) lgkmcnt(0)
	s_barrier
	v_add_u32_e32 v181, v153, v111
	ds_read_b128 v[116:119], v181 offset:0x0
	ds_read_b128 v[120:123], v181 offset:0x1000
	v_add_u32_e32 v181, v154, v111
	ds_read_b128 v[124:127], v181 offset:0x0
	ds_read_b128 v[130:133], v181 offset:0x1000
	ds_read_b128 v[134:137], v181 offset:0x2000
	v_mfma_f32_32x32x16_bf16 v[64:79], v[144:147], v[182:185], v[64:79]
	v_mfma_f32_32x32x16_bf16 v[32:47], v[144:147], v[186:189], v[32:47]
	v_lshl_add_u64 v[244:245], v[98:99], 0, s[2:3]
	v_lshl_add_u64 v[244:245], v[244:245], 0, s[12:13]
	v_readfirstlane_b32 s10, v246
	s_mov_b32 m0, s10
	s_nop 0
	global_load_lds_dwordx4 v[244:245], off
	v_mfma_f32_32x32x16_bf16 v[0:15], v[144:147], v[190:193], v[0:15]
	v_mfma_f32_32x32x16_bf16 v[80:95], v[148:151], v[182:185], v[80:95]
	v_add_u32_e32 v243, 0x2000, v246
	v_lshl_add_u64 v[244:245], v[98:99], 0, s[2:3]
	v_lshl_add_u64 v[244:245], v[244:245], 0, s[16:17]
	v_readfirstlane_b32 s10, v243
	s_mov_b32 m0, s10
	s_nop 0
	global_load_lds_dwordx4 v[244:245], off
	v_mfma_f32_32x32x16_bf16 v[48:63], v[148:151], v[186:189], v[48:63]
	v_mfma_f32_32x32x16_bf16 v[16:31], v[148:151], v[190:193], v[16:31]
	v_add_u32_e32 v243, 0x4000, v246
	v_lshl_add_u64 v[244:245], v[98:99], 0, s[2:3]
	v_lshl_add_u64 v[244:245], v[244:245], 0, s[18:19]
	v_readfirstlane_b32 s10, v243
	s_mov_b32 m0, s10
	s_nop 0
	global_load_lds_dwordx4 v[244:245], off
	v_add_u32_e32 v181, v153, v110
	ds_read_b128 v[144:147], v181 offset:0x0
	ds_read_b128 v[148:151], v181 offset:0x1000
	v_add_u32_e32 v181, v154, v110
	ds_read_b128 v[182:185], v181 offset:0x0
	ds_read_b128 v[186:189], v181 offset:0x1000
	ds_read_b128 v[190:193], v181 offset:0x2000
	s_waitcnt lgkmcnt(5)
	v_mfma_f32_32x32x16_bf16 v[64:79], v[116:119], v[124:127], v[64:79]
	v_mfma_f32_32x32x16_bf16 v[32:47], v[116:119], v[130:133], v[32:47]
	v_add_u32_e32 v243, 0x6000, v246
	s_mov_b64 s[10:11], 0x6a94080
	v_lshl_add_u64 v[244:245], v[96:97], 0, s[2:3]
	v_lshl_add_u64 v[244:245], v[244:245], 0, s[10:11]
	v_readfirstlane_b32 s10, v243
	s_mov_b32 m0, s10
	s_nop 0
	global_load_lds_dwordx4 v[244:245], off
	v_mfma_f32_32x32x16_bf16 v[0:15], v[116:119], v[134:137], v[0:15]
	v_mfma_f32_32x32x16_bf16 v[80:95], v[120:123], v[124:127], v[80:95]
	v_add_u32_e32 v243, 0x8000, v246
	s_mov_b64 s[10:11], 0x6ab4080
	v_lshl_add_u64 v[244:245], v[96:97], 0, s[2:3]
	v_lshl_add_u64 v[244:245], v[244:245], 0, s[10:11]
	v_readfirstlane_b32 s10, v243
	s_mov_b32 m0, s10
	s_nop 0
	global_load_lds_dwordx4 v[244:245], off
	v_mfma_f32_32x32x16_bf16 v[48:63], v[120:123], v[130:133], v[48:63]
	v_mfma_f32_32x32x16_bf16 v[16:31], v[120:123], v[134:137], v[16:31]
	v_add_u32_e32 v243, 0xa000, v246
	s_mov_b64 s[10:11], 0x6ad4080
	v_lshl_add_u64 v[244:245], v[96:97], 0, s[2:3]
	v_lshl_add_u64 v[244:245], v[244:245], 0, s[10:11]
	v_readfirstlane_b32 s10, v243
	s_mov_b32 m0, s10
	s_nop 0
	global_load_lds_dwordx4 v[244:245], off
	v_add_u32_e32 v181, v153, v108
	ds_read_b128 v[116:119], v181 offset:0x0
	ds_read_b128 v[120:123], v181 offset:0x1000
	v_add_u32_e32 v181, v154, v108
	ds_read_b128 v[124:127], v181 offset:0x0
	ds_read_b128 v[130:133], v181 offset:0x1000
	ds_read_b128 v[134:137], v181 offset:0x2000
	s_waitcnt lgkmcnt(5)
	v_mfma_f32_32x32x16_bf16 v[64:79], v[144:147], v[182:185], v[64:79]
	v_mfma_f32_32x32x16_bf16 v[32:47], v[144:147], v[186:189], v[32:47]
	v_add_u32_e32 v243, 0xc000, v246
	s_mov_b64 s[10:11], 0x6af4080
	v_lshl_add_u64 v[244:245], v[96:97], 0, s[2:3]
	v_lshl_add_u64 v[244:245], v[244:245], 0, s[10:11]
	v_readfirstlane_b32 s10, v243
	s_mov_b32 m0, s10
	s_nop 0
	global_load_lds_dwordx4 v[244:245], off
	v_mfma_f32_32x32x16_bf16 v[0:15], v[144:147], v[190:193], v[0:15]
	v_mfma_f32_32x32x16_bf16 v[80:95], v[148:151], v[182:185], v[80:95]
	v_mfma_f32_32x32x16_bf16 v[48:63], v[148:151], v[186:189], v[48:63]
	v_mfma_f32_32x32x16_bf16 v[16:31], v[148:151], v[190:193], v[16:31]
	v_add_u32_e32 v181, v153, v107
	ds_read_b128 v[144:147], v181 offset:0x0
	ds_read_b128 v[148:151], v181 offset:0x1000
	v_add_u32_e32 v181, v154, v107
	ds_read_b128 v[182:185], v181 offset:0x0
	ds_read_b128 v[186:189], v181 offset:0x1000
	ds_read_b128 v[190:193], v181 offset:0x2000
	s_waitcnt lgkmcnt(5)
	v_mfma_f32_32x32x16_bf16 v[64:79], v[116:119], v[124:127], v[64:79]
	v_mfma_f32_32x32x16_bf16 v[32:47], v[116:119], v[130:133], v[32:47]
	v_mfma_f32_32x32x16_bf16 v[0:15], v[116:119], v[134:137], v[0:15]
	v_mfma_f32_32x32x16_bf16 v[80:95], v[120:123], v[124:127], v[80:95]
	v_mfma_f32_32x32x16_bf16 v[48:63], v[120:123], v[130:133], v[48:63]
	v_mfma_f32_32x32x16_bf16 v[16:31], v[120:123], v[134:137], v[16:31]
	s_waitcnt lgkmcnt(0)
	s_add_u32 s2, s2, 0x80
	s_addc_u32 s3, s3, 0
	s_mov_b32 s7, s9
	s_cmpk_lg_i32 s2, 0x780
	s_cbranch_scc1 .LBB0_681
	s_bitcmp1_b32 s7, 0
	s_cselect_b32 s10, 0xe000, 0
	v_add_u32_e32 v153, s10, v114
	v_add_u32_e32 v154, s10, v113
	s_waitcnt vmcnt(0) lgkmcnt(0)
	s_barrier
	v_add_u32_e32 v181, v153, v111
	ds_read_b128 v[116:119], v181 offset:0x0
	ds_read_b128 v[120:123], v181 offset:0x1000
	v_add_u32_e32 v181, v154, v111
	ds_read_b128 v[124:127], v181 offset:0x0
	ds_read_b128 v[130:133], v181 offset:0x1000
	ds_read_b128 v[134:137], v181 offset:0x2000
	v_mfma_f32_32x32x16_bf16 v[64:79], v[144:147], v[182:185], v[64:79]
	v_mfma_f32_32x32x16_bf16 v[32:47], v[144:147], v[186:189], v[32:47]
	v_mfma_f32_32x32x16_bf16 v[0:15], v[144:147], v[190:193], v[0:15]
	v_mfma_f32_32x32x16_bf16 v[80:95], v[148:151], v[182:185], v[80:95]
	v_mfma_f32_32x32x16_bf16 v[48:63], v[148:151], v[186:189], v[48:63]
	v_mfma_f32_32x32x16_bf16 v[16:31], v[148:151], v[190:193], v[16:31]
	v_add_u32_e32 v181, v153, v110
	ds_read_b128 v[144:147], v181 offset:0x0
	ds_read_b128 v[148:151], v181 offset:0x1000
	v_add_u32_e32 v181, v154, v110
	ds_read_b128 v[182:185], v181 offset:0x0
	ds_read_b128 v[186:189], v181 offset:0x1000
	ds_read_b128 v[190:193], v181 offset:0x2000
	s_waitcnt lgkmcnt(5)
	v_mfma_f32_32x32x16_bf16 v[64:79], v[116:119], v[124:127], v[64:79]
	v_mfma_f32_32x32x16_bf16 v[32:47], v[116:119], v[130:133], v[32:47]
	v_mfma_f32_32x32x16_bf16 v[0:15], v[116:119], v[134:137], v[0:15]
	v_mfma_f32_32x32x16_bf16 v[80:95], v[120:123], v[124:127], v[80:95]
	v_mfma_f32_32x32x16_bf16 v[48:63], v[120:123], v[130:133], v[48:63]
	v_mfma_f32_32x32x16_bf16 v[16:31], v[120:123], v[134:137], v[16:31]
	v_add_u32_e32 v181, v153, v108
	ds_read_b128 v[116:119], v181 offset:0x0
	ds_read_b128 v[120:123], v181 offset:0x1000
	v_add_u32_e32 v181, v154, v108
	ds_read_b128 v[124:127], v181 offset:0x0
	ds_read_b128 v[130:133], v181 offset:0x1000
	ds_read_b128 v[134:137], v181 offset:0x2000
	s_waitcnt lgkmcnt(5)
	v_mfma_f32_32x32x16_bf16 v[64:79], v[144:147], v[182:185], v[64:79]
	v_mfma_f32_32x32x16_bf16 v[32:47], v[144:147], v[186:189], v[32:47]
	v_mfma_f32_32x32x16_bf16 v[0:15], v[144:147], v[190:193], v[0:15]
	v_mfma_f32_32x32x16_bf16 v[80:95], v[148:151], v[182:185], v[80:95]
	v_mfma_f32_32x32x16_bf16 v[48:63], v[148:151], v[186:189], v[48:63]
	v_mfma_f32_32x32x16_bf16 v[16:31], v[148:151], v[190:193], v[16:31]
	v_add_u32_e32 v181, v153, v107
	ds_read_b128 v[144:147], v181 offset:0x0
	ds_read_b128 v[148:151], v181 offset:0x1000
	v_add_u32_e32 v181, v154, v107
	ds_read_b128 v[182:185], v181 offset:0x0
	ds_read_b128 v[186:189], v181 offset:0x1000
	ds_read_b128 v[190:193], v181 offset:0x2000
	s_waitcnt lgkmcnt(5)
	v_mfma_f32_32x32x16_bf16 v[64:79], v[116:119], v[124:127], v[64:79]
	v_mfma_f32_32x32x16_bf16 v[32:47], v[116:119], v[130:133], v[32:47]
	v_mfma_f32_32x32x16_bf16 v[0:15], v[116:119], v[134:137], v[0:15]
	v_mfma_f32_32x32x16_bf16 v[80:95], v[120:123], v[124:127], v[80:95]
	v_mfma_f32_32x32x16_bf16 v[48:63], v[120:123], v[130:133], v[48:63]
	v_mfma_f32_32x32x16_bf16 v[16:31], v[120:123], v[134:137], v[16:31]
	s_waitcnt lgkmcnt(0)
	v_mfma_f32_32x32x16_bf16 v[64:79], v[144:147], v[182:185], v[64:79]
	v_mfma_f32_32x32x16_bf16 v[32:47], v[144:147], v[186:189], v[32:47]
	v_mfma_f32_32x32x16_bf16 v[0:15], v[144:147], v[190:193], v[0:15]
	v_mfma_f32_32x32x16_bf16 v[80:95], v[148:151], v[182:185], v[80:95]
	v_mfma_f32_32x32x16_bf16 v[48:63], v[148:151], v[186:189], v[48:63]
	v_mfma_f32_32x32x16_bf16 v[16:31], v[148:151], v[190:193], v[16:31]
	v_add_u32_e32 v96, s4, v106
	v_lshrrev_b32_e32 v128, 4, v101
	v_and_b32_e32 v112, 15, v100
	v_or_b32_e32 v100, v96, v128
	v_add_u32_e32 v105, s8, v105
	v_ashrrev_i32_e32 v101, 31, v100
	v_lshl_or_b32 v98, v112, 2, v105
	v_lshlrev_b64 v[106:107], 12, v[100:101]
	v_ashrrev_i32_e32 v99, 31, v98
	v_lshl_add_u64 v[106:107], s[40:41], 0, v[106:107]
	v_lshl_add_u64 v[110:111], v[98:99], 2, v[106:107]
	s_barrier
	v_add_co_u32_e32 v182, vcc, 0x20000, v110
	s_nop 1
	v_addc_co_u32_e32 v183, vcc, 0, v111, vcc
	global_load_dwordx4 v[184:187], v[182:183], off
	v_add_co_u32_e32 v182, vcc, 0x4000, v182
	s_nop 1
	v_addc_co_u32_e32 v183, vcc, 0, v183, vcc
	global_load_dwordx4 v[188:191], v[182:183], off
	v_add_co_u32_e32 v182, vcc, 0x4000, v182
	s_nop 1
	v_addc_co_u32_e32 v183, vcc, 0, v183, vcc
	global_load_dwordx4 v[192:195], v[182:183], off
	v_add_co_u32_e32 v182, vcc, 0x4000, v182
	s_nop 1
	v_addc_co_u32_e32 v183, vcc, 0, v183, vcc
	global_load_dwordx4 v[116:119], v[182:183], off
	v_add_co_u32_e32 v182, vcc, 0x4000, v182
	s_nop 1
	v_addc_co_u32_e32 v183, vcc, 0, v183, vcc
	global_load_dwordx4 v[120:123], v[182:183], off
	v_add_co_u32_e32 v182, vcc, 0x4000, v182
	s_nop 1
	v_addc_co_u32_e32 v183, vcc, 0, v183, vcc
	global_load_dwordx4 v[124:127], v[182:183], off
	v_add_co_u32_e32 v182, vcc, 0x4000, v182
	s_nop 1
	v_addc_co_u32_e32 v183, vcc, 0, v183, vcc
	global_load_dwordx4 v[130:133], v[182:183], off
	v_add_co_u32_e32 v182, vcc, 0x4000, v182
	s_nop 1
	v_addc_co_u32_e32 v183, vcc, 0, v183, vcc
	global_load_dwordx4 v[134:137], v[182:183], off
	s_movk_i32 s2, 0x2400
	s_cmp_lt_i32 s5, 22
	v_mul_lo_u32 v97, v103, s2
	s_cselect_b64 s[2:3], -1, 0
	s_cmp_gt_i32 s5, 21
	s_movk_i32 s5, 0x110
	v_and_b32_e32 v103, 16, v104
	v_mad_u32_u24 v104, v102, s5, v97
	v_add_u32_e32 v113, 0xfffff000, v96
	v_cndmask_b32_e64 v102, 0, 1, s[2:3]
	s_cselect_b64 s[2:3], -1, 0
	s_add_i32 s7, s4, 0xfffff000
	v_add_u32_e32 v104, v104, v103
	ds_write_b128 v104, v[64:67]
	ds_write_b128 v104, v[68:71] offset:32
	ds_write_b128 v104, v[72:75] offset:64
	ds_write_b128 v104, v[76:79] offset:96
	ds_write_b128 v104, v[80:83] offset:128
	ds_write_b128 v104, v[84:87] offset:160
	ds_write_b128 v104, v[88:91] offset:192
	ds_write_b128 v104, v[92:95] offset:224
	v_xor_b32_e32 v64, s7, v113
	s_movk_i32 s4, 0x400
	v_lshl_or_b32 v97, v112, 4, v97
	v_cmp_gt_u32_e32 vcc, s4, v64
	v_mad_u32_u24 v115, v128, s5, v97
	s_and_b64 s[4:5], s[2:3], vcc
	v_cndmask_b32_e64 v71, 0, 1, s[4:5]
	s_movk_i32 s4, 0x1000
	v_cmp_gt_i32_e32 vcc, s4, v100
	v_subrev_u32_e32 v114, s8, v98
	v_lshl_add_u32 v103, v114, 2, v167
	v_cndmask_b32_e32 v64, v71, v102, vcc
	v_and_b32_e32 v64, 1, v64
	v_cmp_eq_u32_e32 vcc, 1, v64
	v_ashrrev_i32_e32 v68, 6, v105
	s_mov_b32 s4, 0xc000
	v_cndmask_b32_e64 v64, v171, 0, vcc
	v_add_u32_e32 v70, v103, v64
	ds_read_b128 v[64:67], v115
	ds_read_b128 v[72:75], v70
	v_cmp_eq_u32_e64 s[36:37], 0, v112
	v_mad_i64_i32 v[68:69], s[4:5], v68, s4, 0
	s_and_b64 vcc, exec, s[0:1]
	s_waitcnt lgkmcnt(0)
	v_pk_fma_f32 v[66:67], v[66:67], v[74:75], v[200:201]
	v_pk_fma_f32 v[64:65], v[64:65], v[72:73], v[198:199]
	global_store_dwordx4 v[110:111], v[64:67], off
	s_cbranch_vccnz .LBB0_686
	ds_read_b128 v[72:75], v70 offset:2048
	v_lshlrev_b64 v[76:77], 10, v[100:101]
	v_lshl_add_u64 v[76:77], v[76:77], 1, s[42:43]
	v_lshl_add_u64 v[76:77], v[98:99], 1, v[76:77]
	s_waitcnt lgkmcnt(0)
	v_pk_mul_f32 v[72:73], v[64:65], v[72:73]
	v_pk_mul_f32 v[64:65], v[64:65], v[64:65]
	v_pk_mul_f32 v[74:75], v[66:67], v[74:75]
	v_pk_mul_f32 v[66:67], v[66:67], v[66:67]
	v_add_f32_e32 v64, v64, v65
	v_add_f32_e32 v64, v66, v64
	v_add_f32_e32 v64, v67, v64
	v_cvt_pk_bf16_f32 v72, v72, v73
	v_cvt_pk_bf16_f32 v73, v74, v75
	v_add_f32_dpp v64, v64, v64 quad_perm:[1,0,3,2] row_mask:0xf bank_mask:0xf bound_ctrl:1
	global_store_dwordx2 v[76:77], v[72:73], off
	s_nop 0
	v_add_f32_dpp v64, v64, v64 quad_perm:[2,3,0,1] row_mask:0xf bank_mask:0xf bound_ctrl:1
	s_nop 1
	v_add_f32_dpp v64, v64, v64 row_half_mirror row_mask:0xf bank_mask:0xf bound_ctrl:1
	s_nop 1
	v_mov_b32_dpp v65, v64 row_mirror row_mask:0xf bank_mask:0xf bound_ctrl:1
	s_and_saveexec_b64 s[4:5], s[36:37]
	s_cbranch_execz .LBB0_685
	v_lshl_add_u64 v[66:67], s[52:53], 0, v[68:69]
	v_lshl_add_u64 v[66:67], v[100:101], 2, v[66:67]
	v_add_f32_e32 v64, v64, v65
	global_store_dword v[66:67], v64, off

.LBB0_832:
	s_or_b64 exec, exec, s[0:1]
	v_ashrrev_i32_e32 v0, 6, v4
	v_lshrrev_b32_e32 v1, 30, v0
	v_add_u32_e32 v1, v0, v1
	v_ashrrev_i32_e32 v5, 2, v1
	v_mul_i32_i24_e32 v1, 4, v5
	v_ashrrev_i32_e32 v8, 3, v4
	v_sub_u32_e32 v13, v0, v1
	v_lshrrev_b32_e32 v14, 4, v4
	v_add_u32_e32 v0, s26, v8
	v_xor_b32_e32 v6, v14, v4
	v_ashrrev_i32_e32 v1, 31, v0
	s_add_i32 s1, s26, 0xbf
	s_ashr_i32 s0, s2, 6
	v_lshlrev_b64 v[0:1], 11, v[0:1]
	v_lshlrev_b32_e32 v6, 4, v6
	v_cmp_gt_i32_e32 vcc, s31, v4
	v_mov_b32_e32 v10, s1
	v_mov_b32_e32 v11, s26
	s_lshl_b32 s0, s0, 8
	v_lshl_add_u64 v[2:3], s[52:53], 0, v[0:1]
	v_and_b32_e32 v128, 0x70, v6
	v_cndmask_b32_e32 v10, v10, v11, vcc
	v_lshl_add_u64 v[6:7], v[2:3], 0, v[128:129]
	v_add_u32_e32 v2, s0, v8
	v_add_u32_e32 v11, 0xfffff000, v10
	v_ashrrev_i32_e32 v3, 31, v2
	v_lshrrev_b32_e32 v11, 10, v11
	s_movk_i32 s1, 0xc00
	v_lshlrev_b64 v[2:3], 11, v[2:3]
	v_mad_u32_u24 v11, v11, s1, s1
	s_movk_i32 s1, 0xfff
	v_lshl_add_u64 v[8:9], s[64:65], 0, v[2:3]
	v_cmp_lt_i32_e32 vcc, s1, v10
	v_lshl_add_u64 v[8:9], v[8:9], 0, v[128:129]
	s_ashr_i32 s1, s0, 31
	v_cndmask_b32_e32 v128, 0, v11, vcc
	v_lshl_add_u64 v[10:11], v[128:129], 2, s[56:57]
	v_lshl_add_u64 v[10:11], s[0:1], 2, v[10:11]
	v_lshlrev_b32_sdwa v128, v176, v4 dst_sel:DWORD dst_unused:UNUSED_PAD src0_sel:DWORD src1_sel:BYTE_0
	v_lshl_add_u64 v[10:11], v[10:11], 0, v[128:129]
	global_load_dword v10, v[10:11], off
	v_lshlrev_b32_e32 v102, 4, v4
	v_add_u32_e32 v15, 0x2000, v102
	v_readfirstlane_b32 s1, v102
	v_lshl_add_u32 v11, v4, 2, v177
	s_mov_b32 m0, s1
	s_mov_b64 s[2:3], 0x20000
	v_readfirstlane_b32 s1, v15
	s_mov_b64 s[6:7], 0x40000
	v_and_b32_e32 v101, 31, v4
	v_mul_i32_i24_e32 v104, 0x60, v5
	v_lshrrev_b32_e32 v12, 5, v4
	v_or_b32_e32 v5, v104, v101
	v_bfe_u32 v100, v4, 5, 1
	v_lshlrev_b32_e32 v106, 7, v5
	v_lshlrev_b32_e32 v103, 6, v13
	v_mov_b32_e32 v48, 0
	s_mov_b32 s5, 0
	v_mov_b32_e32 v49, v48
	v_mov_b32_e32 v50, v48
	v_mov_b32_e32 v51, v48
	v_mov_b32_e32 v52, v48
	v_mov_b32_e32 v53, v48
	v_mov_b32_e32 v54, v48
	v_mov_b32_e32 v55, v48
	v_mov_b32_e32 v56, v48
	v_mov_b32_e32 v57, v48
	v_mov_b32_e32 v58, v48
	v_mov_b32_e32 v59, v48
	v_mov_b32_e32 v60, v48
	v_mov_b32_e32 v61, v48
	v_mov_b32_e32 v62, v48
	v_mov_b32_e32 v63, v48
	s_waitcnt vmcnt(10)
	v_mov_b32_e32 v80, v48
	v_mov_b32_e32 v81, v48
	v_mov_b32_e32 v82, v48
	v_mov_b32_e32 v83, v48
	s_waitcnt vmcnt(9)
	v_mov_b32_e32 v84, v48
	v_mov_b32_e32 v85, v48
	v_mov_b32_e32 v86, v48
	v_mov_b32_e32 v87, v48
	v_mov_b32_e32 v88, v48
	v_mov_b32_e32 v89, v48
	v_mov_b32_e32 v90, v48
	v_mov_b32_e32 v91, v48
	v_mov_b32_e32 v92, v48
	v_mov_b32_e32 v93, v48
	v_mov_b32_e32 v94, v48
	v_mov_b32_e32 v95, v48
	v_mov_b32_e32 v13, v48
	v_mov_b32_e32 v15, v48
	v_mov_b32_e32 v64, v48
	v_mov_b32_e32 v65, v48
	v_mov_b32_e32 v66, v48
	v_mov_b32_e32 v67, v48
	v_mov_b32_e32 v68, v48
	v_mov_b32_e32 v69, v48
	v_mov_b32_e32 v70, v48
	v_mov_b32_e32 v71, v48
	v_mov_b32_e32 v72, v48
	v_mov_b32_e32 v73, v48
	v_mov_b32_e32 v74, v48
	v_mov_b32_e32 v75, v48
	v_mov_b32_e32 v76, v48
	v_mov_b32_e32 v77, v48
	v_mov_b32_e32 v78, v48
	v_mov_b32_e32 v79, v48
	v_mov_b32_e32 v32, v48
	v_mov_b32_e32 v33, v48
	v_mov_b32_e32 v34, v48
	v_mov_b32_e32 v35, v48
	v_mov_b32_e32 v36, v48
	v_mov_b32_e32 v37, v48
	v_mov_b32_e32 v38, v48
	v_mov_b32_e32 v39, v48
	v_mov_b32_e32 v40, v48
	v_mov_b32_e32 v41, v48
	v_mov_b32_e32 v42, v48
	v_mov_b32_e32 v43, v48
	v_mov_b32_e32 v44, v48
	s_waitcnt vmcnt(0)
	ds_write_b32 v11, v10
	v_lshl_add_u64 v[10:11], v[6:7], 0, s[2:3]
	s_mov_b32 m0, s1
	v_lshl_add_u64 v[6:7], v[6:7], 0, s[6:7]
	v_add_u32_e32 v10, 0x4000, v102
	v_mov_b32_e32 v11, v48
	v_readfirstlane_b32 s1, v10
	s_mov_b32 m0, s1
	v_add_u32_e32 v10, 0x8000, v102
	v_add_u32_e32 v6, 0x6000, v102
	v_mov_b32_e32 v45, v48
	v_readfirstlane_b32 s1, v6
	s_mov_b32 m0, s1
	v_readfirstlane_b32 s1, v10
	v_add_u32_e32 v10, 0xa000, v102
	v_lshl_add_u64 v[6:7], v[8:9], 0, s[2:3]
	s_mov_b32 m0, s1
	v_readfirstlane_b32 s1, v10
	v_lshl_add_u64 v[6:7], v[8:9], 0, s[6:7]
	s_mov_b32 m0, s1
	s_mov_b64 s[2:3], 0x60000
	v_lshl_add_u64 v[6:7], v[8:9], 0, s[2:3]
	v_add_u32_e32 v8, 0xc000, v102
	s_mov_b64 s[2:3], 0
	v_readfirstlane_b32 s1, v8
	s_mov_b32 m0, s1
	v_mov_b32_e32 v8, v48
	v_bfe_u32 v6, v4, 1, 3
	v_bitop3_b32 v5, v12, v6, 1 bitop3:0x6c
	v_lshlrev_b32_e32 v108, 4, v5
	v_bitop3_b32 v5, v100, v6, 2 bitop3:0x36
	v_bitop3_b32 v4, v14, 7, v4 bitop3:0x48
	v_or_b32_e32 v7, v103, v101
	v_lshlrev_b32_e32 v107, 4, v5
	v_bitop3_b32 v5, v100, v6, 4 bitop3:0x36
	v_lshlrev_b32_e32 v4, 4, v4
	v_lshlrev_b32_e32 v105, 7, v7
	v_lshlrev_b32_e32 v110, 4, v5
	v_bitop3_b32 v5, v100, v6, 6 bitop3:0x36
	v_or_b32_e32 v2, v2, v4
	v_or_b32_e32 v0, v0, v4
	v_lshlrev_b32_e32 v109, 4, v5
	v_add_u32_e32 v111, 0x6000, v105
	v_lshl_add_u64 v[96:97], s[66:67], 0, v[2:3]
	v_lshl_add_u64 v[98:99], s[50:51], 0, v[0:1]
	v_mov_b32_e32 v0, v48
	v_mov_b32_e32 v1, v48
	v_mov_b32_e32 v2, v48
	v_mov_b32_e32 v3, v48
	v_mov_b32_e32 v4, v48
	v_mov_b32_e32 v5, v48
	v_mov_b32_e32 v6, v48
	v_mov_b32_e32 v7, v48
	v_mov_b32_e32 v9, v48
	v_mov_b32_e32 v10, v48
	v_mov_b32_e32 v12, v48
	v_mov_b32_e32 v14, v48
	v_mov_b32_e32 v46, v48
	v_mov_b32_e32 v47, v48
	v_mov_b32_e32 v16, v48
	v_mov_b32_e32 v17, v48
	v_mov_b32_e32 v18, v48
	v_mov_b32_e32 v19, v48
	v_mov_b32_e32 v20, v48
	v_mov_b32_e32 v21, v48
	v_mov_b32_e32 v22, v48
	v_mov_b32_e32 v23, v48
	v_mov_b32_e32 v24, v48
	v_mov_b32_e32 v25, v48
	v_mov_b32_e32 v26, v48
	v_mov_b32_e32 v27, v48
	v_mov_b32_e32 v28, v48
	v_mov_b32_e32 v29, v48
	v_mov_b32_e32 v30, v48
	v_mov_b32_e32 v31, v48
	s_mov_b64 s[14:15], 0x6fb4080
	s_mov_b64 s[16:17], 0x6fd4080
	s_add_i32 s1, s5, 1
	s_bitcmp1_b32 s1, 0
	s_cselect_b32 s6, 0xe000, 0
	v_add_u32_e32 v246, s6, v102
	s_bitcmp1_b32 s5, 0
	s_cselect_b32 s6, 0xe000, 0
	v_add_u32_e32 v153, s6, v111
	v_add_u32_e32 v154, s6, v106
	s_waitcnt vmcnt(0) lgkmcnt(0)
	s_barrier
	v_add_u32_e32 v181, v153, v108
	ds_read_b128 v[112:115], v181 offset:0x0
	ds_read_b128 v[116:119], v181 offset:0x1000
	v_add_u32_e32 v181, v154, v108
	ds_read_b128 v[120:123], v181 offset:0x0
	ds_read_b128 v[124:127], v181 offset:0x1000
	ds_read_b128 v[130:133], v181 offset:0x2000
	v_add_u32_e32 v181, v153, v107
	ds_read_b128 v[134:137], v181 offset:0x0
	ds_read_b128 v[144:147], v181 offset:0x1000
	v_add_u32_e32 v181, v154, v107
	ds_read_b128 v[148:151], v181 offset:0x0
	ds_read_b128 v[182:185], v181 offset:0x1000
	ds_read_b128 v[186:189], v181 offset:0x2000
	s_waitcnt lgkmcnt(5)
	v_mfma_f32_32x32x16_bf16 v[80:95], v[112:115], v[120:123], v[80:95]
	v_mfma_f32_32x32x16_bf16 v[48:63], v[112:115], v[124:127], v[48:63]
	v_lshl_add_u64 v[244:245], v[98:99], 0, s[2:3]
	v_lshl_add_u64 v[244:245], v[244:245], 0, s[90:91]
	v_readfirstlane_b32 s6, v246
	s_mov_b32 m0, s6
	s_nop 0
	global_load_lds_dwordx4 v[244:245], off
	v_mfma_f32_32x32x16_bf16 v[0:15], v[112:115], v[130:133], v[0:15]
	v_mfma_f32_32x32x16_bf16 v[64:79], v[116:119], v[120:123], v[64:79]
	v_add_u32_e32 v243, 0x2000, v246
	v_lshl_add_u64 v[244:245], v[98:99], 0, s[2:3]
	v_lshl_add_u64 v[244:245], v[244:245], 0, s[14:15]
	v_readfirstlane_b32 s6, v243
	s_mov_b32 m0, s6
	s_nop 0
	global_load_lds_dwordx4 v[244:245], off
	v_mfma_f32_32x32x16_bf16 v[32:47], v[116:119], v[124:127], v[32:47]
	v_mfma_f32_32x32x16_bf16 v[16:31], v[116:119], v[130:133], v[16:31]
	v_add_u32_e32 v243, 0x4000, v246
	v_lshl_add_u64 v[244:245], v[98:99], 0, s[2:3]
	v_lshl_add_u64 v[244:245], v[244:245], 0, s[16:17]
	v_readfirstlane_b32 s6, v243
	s_mov_b32 m0, s6
	s_nop 0
	global_load_lds_dwordx4 v[244:245], off
	v_add_u32_e32 v181, v153, v110
	ds_read_b128 v[112:115], v181 offset:0x0
	ds_read_b128 v[116:119], v181 offset:0x1000
	v_add_u32_e32 v181, v154, v110
	ds_read_b128 v[120:123], v181 offset:0x0
	ds_read_b128 v[124:127], v181 offset:0x1000
	ds_read_b128 v[130:133], v181 offset:0x2000
	s_waitcnt lgkmcnt(5)
	v_mfma_f32_32x32x16_bf16 v[80:95], v[134:137], v[148:151], v[80:95]
	v_mfma_f32_32x32x16_bf16 v[48:63], v[134:137], v[182:185], v[48:63]
	v_add_u32_e32 v243, 0x6000, v246
	s_mov_b64 s[6:7], 0x5314080
	v_lshl_add_u64 v[244:245], v[96:97], 0, s[2:3]
	v_lshl_add_u64 v[244:245], v[244:245], 0, s[6:7]
	v_readfirstlane_b32 s6, v243
	s_mov_b32 m0, s6
	s_nop 0
	global_load_lds_dwordx4 v[244:245], off
	v_mfma_f32_32x32x16_bf16 v[0:15], v[134:137], v[186:189], v[0:15]
	v_mfma_f32_32x32x16_bf16 v[64:79], v[144:147], v[148:151], v[64:79]
	v_add_u32_e32 v243, 0x8000, v246
	s_mov_b64 s[6:7], 0x5334080
	v_lshl_add_u64 v[244:245], v[96:97], 0, s[2:3]
	v_lshl_add_u64 v[244:245], v[244:245], 0, s[6:7]
	v_readfirstlane_b32 s6, v243
	s_mov_b32 m0, s6
	s_nop 0
	global_load_lds_dwordx4 v[244:245], off
	v_mfma_f32_32x32x16_bf16 v[32:47], v[144:147], v[182:185], v[32:47]
	v_mfma_f32_32x32x16_bf16 v[16:31], v[144:147], v[186:189], v[16:31]
	v_add_u32_e32 v243, 0xa000, v246
	s_mov_b64 s[6:7], 0x5354080
	v_lshl_add_u64 v[244:245], v[96:97], 0, s[2:3]
	v_lshl_add_u64 v[244:245], v[244:245], 0, s[6:7]
	v_readfirstlane_b32 s6, v243
	s_mov_b32 m0, s6
	s_nop 0
	global_load_lds_dwordx4 v[244:245], off
	v_add_u32_e32 v181, v153, v109
	ds_read_b128 v[134:137], v181 offset:0x0
	ds_read_b128 v[144:147], v181 offset:0x1000
	v_add_u32_e32 v181, v154, v109
	ds_read_b128 v[148:151], v181 offset:0x0
	ds_read_b128 v[182:185], v181 offset:0x1000
	ds_read_b128 v[186:189], v181 offset:0x2000
	s_waitcnt lgkmcnt(5)
	v_mfma_f32_32x32x16_bf16 v[80:95], v[112:115], v[120:123], v[80:95]
	v_mfma_f32_32x32x16_bf16 v[48:63], v[112:115], v[124:127], v[48:63]
	v_add_u32_e32 v243, 0xc000, v246
	s_mov_b64 s[6:7], 0x5374080
	v_lshl_add_u64 v[244:245], v[96:97], 0, s[2:3]
	v_lshl_add_u64 v[244:245], v[244:245], 0, s[6:7]
	v_readfirstlane_b32 s6, v243
	s_mov_b32 m0, s6
	s_nop 0
	global_load_lds_dwordx4 v[244:245], off
	v_mfma_f32_32x32x16_bf16 v[0:15], v[112:115], v[130:133], v[0:15]
	v_mfma_f32_32x32x16_bf16 v[64:79], v[116:119], v[120:123], v[64:79]
	v_mfma_f32_32x32x16_bf16 v[32:47], v[116:119], v[124:127], v[32:47]
	v_mfma_f32_32x32x16_bf16 v[16:31], v[116:119], v[130:133], v[16:31]
	s_waitcnt lgkmcnt(0)
	s_add_u32 s2, s2, 0x80
	s_addc_u32 s3, s3, 0
	s_mov_b32 s5, s1
.LBB0_833:
	s_add_i32 s1, s5, 1
	s_bitcmp1_b32 s1, 0
	s_cselect_b32 s6, 0xe000, 0
	v_add_u32_e32 v246, s6, v102
	s_bitcmp1_b32 s5, 0
	s_cselect_b32 s6, 0xe000, 0
	v_add_u32_e32 v153, s6, v111
	v_add_u32_e32 v154, s6, v106
	s_waitcnt vmcnt(0) lgkmcnt(0)
	s_barrier
	v_add_u32_e32 v181, v153, v108
	ds_read_b128 v[112:115], v181 offset:0x0
	ds_read_b128 v[116:119], v181 offset:0x1000
	v_add_u32_e32 v181, v154, v108
	ds_read_b128 v[120:123], v181 offset:0x0
	ds_read_b128 v[124:127], v181 offset:0x1000
	ds_read_b128 v[130:133], v181 offset:0x2000
	v_mfma_f32_32x32x16_bf16 v[80:95], v[134:137], v[148:151], v[80:95]
	v_mfma_f32_32x32x16_bf16 v[48:63], v[134:137], v[182:185], v[48:63]
	v_lshl_add_u64 v[244:245], v[98:99], 0, s[2:3]
	v_lshl_add_u64 v[244:245], v[244:245], 0, s[90:91]
	v_readfirstlane_b32 s6, v246
	s_mov_b32 m0, s6
	s_nop 0
	global_load_lds_dwordx4 v[244:245], off
	v_mfma_f32_32x32x16_bf16 v[0:15], v[134:137], v[186:189], v[0:15]
	v_mfma_f32_32x32x16_bf16 v[64:79], v[144:147], v[148:151], v[64:79]
	v_add_u32_e32 v243, 0x2000, v246
	v_lshl_add_u64 v[244:245], v[98:99], 0, s[2:3]
	v_lshl_add_u64 v[244:245], v[244:245], 0, s[14:15]
	v_readfirstlane_b32 s6, v243
	s_mov_b32 m0, s6
	s_nop 0
	global_load_lds_dwordx4 v[244:245], off
	v_mfma_f32_32x32x16_bf16 v[32:47], v[144:147], v[182:185], v[32:47]
	v_mfma_f32_32x32x16_bf16 v[16:31], v[144:147], v[186:189], v[16:31]
	v_add_u32_e32 v243, 0x4000, v246
	v_lshl_add_u64 v[244:245], v[98:99], 0, s[2:3]
	v_lshl_add_u64 v[244:245], v[244:245], 0, s[16:17]
	v_readfirstlane_b32 s6, v243
	s_mov_b32 m0, s6
	s_nop 0
	global_load_lds_dwordx4 v[244:245], off
	v_add_u32_e32 v181, v153, v107
	ds_read_b128 v[134:137], v181 offset:0x0
	ds_read_b128 v[144:147], v181 offset:0x1000
	v_add_u32_e32 v181, v154, v107
	ds_read_b128 v[148:151], v181 offset:0x0
	ds_read_b128 v[182:185], v181 offset:0x1000
	ds_read_b128 v[186:189], v181 offset:0x2000
	s_waitcnt lgkmcnt(5)
	v_mfma_f32_32x32x16_bf16 v[80:95], v[112:115], v[120:123], v[80:95]
	v_mfma_f32_32x32x16_bf16 v[48:63], v[112:115], v[124:127], v[48:63]
	v_add_u32_e32 v243, 0x6000, v246
	s_mov_b64 s[6:7], 0x5314080
	v_lshl_add_u64 v[244:245], v[96:97], 0, s[2:3]
	v_lshl_add_u64 v[244:245], v[244:245], 0, s[6:7]
	v_readfirstlane_b32 s6, v243
	s_mov_b32 m0, s6
	s_nop 0
	global_load_lds_dwordx4 v[244:245], off
	v_mfma_f32_32x32x16_bf16 v[0:15], v[112:115], v[130:133], v[0:15]
	v_mfma_f32_32x32x16_bf16 v[64:79], v[116:119], v[120:123], v[64:79]
	v_add_u32_e32 v243, 0x8000, v246
	s_mov_b64 s[6:7], 0x5334080
	v_lshl_add_u64 v[244:245], v[96:97], 0, s[2:3]
	v_lshl_add_u64 v[244:245], v[244:245], 0, s[6:7]
	v_readfirstlane_b32 s6, v243
	s_mov_b32 m0, s6
	s_nop 0
	global_load_lds_dwordx4 v[244:245], off
	v_mfma_f32_32x32x16_bf16 v[32:47], v[116:119], v[124:127], v[32:47]
	v_mfma_f32_32x32x16_bf16 v[16:31], v[116:119], v[130:133], v[16:31]
	v_add_u32_e32 v243, 0xa000, v246
	s_mov_b64 s[6:7], 0x5354080
	v_lshl_add_u64 v[244:245], v[96:97], 0, s[2:3]
	v_lshl_add_u64 v[244:245], v[244:245], 0, s[6:7]
	v_readfirstlane_b32 s6, v243
	s_mov_b32 m0, s6
	s_nop 0
	global_load_lds_dwordx4 v[244:245], off
	v_add_u32_e32 v181, v153, v110
	ds_read_b128 v[112:115], v181 offset:0x0
	ds_read_b128 v[116:119], v181 offset:0x1000
	v_add_u32_e32 v181, v154, v110
	ds_read_b128 v[120:123], v181 offset:0x0
	ds_read_b128 v[124:127], v181 offset:0x1000
	ds_read_b128 v[130:133], v181 offset:0x2000
	s_waitcnt lgkmcnt(5)
	v_mfma_f32_32x32x16_bf16 v[80:95], v[134:137], v[148:151], v[80:95]
	v_mfma_f32_32x32x16_bf16 v[48:63], v[134:137], v[182:185], v[48:63]
	v_add_u32_e32 v243, 0xc000, v246
	s_mov_b64 s[6:7], 0x5374080
	v_lshl_add_u64 v[244:245], v[96:97], 0, s[2:3]
	v_lshl_add_u64 v[244:245], v[244:245], 0, s[6:7]
	v_readfirstlane_b32 s6, v243
	s_mov_b32 m0, s6
	s_nop 0
	global_load_lds_dwordx4 v[244:245], off
	v_mfma_f32_32x32x16_bf16 v[0:15], v[134:137], v[186:189], v[0:15]
	v_mfma_f32_32x32x16_bf16 v[64:79], v[144:147], v[148:151], v[64:79]
	v_mfma_f32_32x32x16_bf16 v[32:47], v[144:147], v[182:185], v[32:47]
	v_mfma_f32_32x32x16_bf16 v[16:31], v[144:147], v[186:189], v[16:31]
	v_add_u32_e32 v181, v153, v109
	ds_read_b128 v[134:137], v181 offset:0x0
	ds_read_b128 v[144:147], v181 offset:0x1000
	v_add_u32_e32 v181, v154, v109
	ds_read_b128 v[148:151], v181 offset:0x0
	ds_read_b128 v[182:185], v181 offset:0x1000
	ds_read_b128 v[186:189], v181 offset:0x2000
	s_waitcnt lgkmcnt(5)
	v_mfma_f32_32x32x16_bf16 v[80:95], v[112:115], v[120:123], v[80:95]
	v_mfma_f32_32x32x16_bf16 v[48:63], v[112:115], v[124:127], v[48:63]
	v_mfma_f32_32x32x16_bf16 v[0:15], v[112:115], v[130:133], v[0:15]
	v_mfma_f32_32x32x16_bf16 v[64:79], v[116:119], v[120:123], v[64:79]
	v_mfma_f32_32x32x16_bf16 v[32:47], v[116:119], v[124:127], v[32:47]
	v_mfma_f32_32x32x16_bf16 v[16:31], v[116:119], v[130:133], v[16:31]
	s_waitcnt lgkmcnt(0)
	s_add_u32 s2, s2, 0x80
	s_addc_u32 s3, s3, 0
	s_mov_b32 s5, s1
	s_cmpk_lg_i32 s2, 0x780
	s_cbranch_scc1 .LBB0_833
	s_bitcmp1_b32 s5, 0
	s_cselect_b32 s6, 0xe000, 0
	v_add_u32_e32 v153, s6, v111
	v_add_u32_e32 v154, s6, v106
	s_waitcnt vmcnt(0) lgkmcnt(0)
	s_barrier
	v_add_u32_e32 v181, v153, v108
	ds_read_b128 v[112:115], v181 offset:0x0
	ds_read_b128 v[116:119], v181 offset:0x1000
	v_add_u32_e32 v181, v154, v108
	ds_read_b128 v[120:123], v181 offset:0x0
	ds_read_b128 v[124:127], v181 offset:0x1000
	ds_read_b128 v[130:133], v181 offset:0x2000
	v_mfma_f32_32x32x16_bf16 v[80:95], v[134:137], v[148:151], v[80:95]
	v_mfma_f32_32x32x16_bf16 v[48:63], v[134:137], v[182:185], v[48:63]
	v_mfma_f32_32x32x16_bf16 v[0:15], v[134:137], v[186:189], v[0:15]
	v_mfma_f32_32x32x16_bf16 v[64:79], v[144:147], v[148:151], v[64:79]
	v_mfma_f32_32x32x16_bf16 v[32:47], v[144:147], v[182:185], v[32:47]
	v_mfma_f32_32x32x16_bf16 v[16:31], v[144:147], v[186:189], v[16:31]
	v_add_u32_e32 v181, v153, v107
	ds_read_b128 v[134:137], v181 offset:0x0
	ds_read_b128 v[144:147], v181 offset:0x1000
	v_add_u32_e32 v181, v154, v107
	ds_read_b128 v[148:151], v181 offset:0x0
	ds_read_b128 v[182:185], v181 offset:0x1000
	ds_read_b128 v[186:189], v181 offset:0x2000
	s_waitcnt lgkmcnt(5)
	v_mfma_f32_32x32x16_bf16 v[80:95], v[112:115], v[120:123], v[80:95]
	v_mfma_f32_32x32x16_bf16 v[48:63], v[112:115], v[124:127], v[48:63]
	v_mfma_f32_32x32x16_bf16 v[0:15], v[112:115], v[130:133], v[0:15]
	v_mfma_f32_32x32x16_bf16 v[64:79], v[116:119], v[120:123], v[64:79]
	v_mfma_f32_32x32x16_bf16 v[32:47], v[116:119], v[124:127], v[32:47]
	v_mfma_f32_32x32x16_bf16 v[16:31], v[116:119], v[130:133], v[16:31]
	v_add_u32_e32 v181, v153, v110
	ds_read_b128 v[112:115], v181 offset:0x0
	ds_read_b128 v[116:119], v181 offset:0x1000
	v_add_u32_e32 v181, v154, v110
	ds_read_b128 v[120:123], v181 offset:0x0
	ds_read_b128 v[124:127], v181 offset:0x1000
	ds_read_b128 v[130:133], v181 offset:0x2000
	s_waitcnt lgkmcnt(5)
	v_mfma_f32_32x32x16_bf16 v[80:95], v[134:137], v[148:151], v[80:95]
	v_mfma_f32_32x32x16_bf16 v[48:63], v[134:137], v[182:185], v[48:63]
	v_mfma_f32_32x32x16_bf16 v[0:15], v[134:137], v[186:189], v[0:15]
	v_mfma_f32_32x32x16_bf16 v[64:79], v[144:147], v[148:151], v[64:79]
	v_mfma_f32_32x32x16_bf16 v[32:47], v[144:147], v[182:185], v[32:47]
	v_mfma_f32_32x32x16_bf16 v[16:31], v[144:147], v[186:189], v[16:31]
	v_add_u32_e32 v181, v153, v109
	ds_read_b128 v[134:137], v181 offset:0x0
	ds_read_b128 v[144:147], v181 offset:0x1000
	v_add_u32_e32 v181, v154, v109
	ds_read_b128 v[148:151], v181 offset:0x0
	ds_read_b128 v[182:185], v181 offset:0x1000
	ds_read_b128 v[186:189], v181 offset:0x2000
	s_waitcnt lgkmcnt(5)
	v_mfma_f32_32x32x16_bf16 v[80:95], v[112:115], v[120:123], v[80:95]
	v_mfma_f32_32x32x16_bf16 v[48:63], v[112:115], v[124:127], v[48:63]
	v_mfma_f32_32x32x16_bf16 v[0:15], v[112:115], v[130:133], v[0:15]
	v_mfma_f32_32x32x16_bf16 v[64:79], v[116:119], v[120:123], v[64:79]
	v_mfma_f32_32x32x16_bf16 v[32:47], v[116:119], v[124:127], v[32:47]
	v_mfma_f32_32x32x16_bf16 v[16:31], v[116:119], v[130:133], v[16:31]
	s_waitcnt lgkmcnt(0)
	v_mfma_f32_32x32x16_bf16 v[80:95], v[134:137], v[148:151], v[80:95]
	v_mfma_f32_32x32x16_bf16 v[48:63], v[134:137], v[182:185], v[48:63]
	v_mfma_f32_32x32x16_bf16 v[0:15], v[134:137], v[186:189], v[0:15]
	v_mfma_f32_32x32x16_bf16 v[64:79], v[144:147], v[148:151], v[64:79]
	v_mfma_f32_32x32x16_bf16 v[32:47], v[144:147], v[182:185], v[32:47]
	v_mfma_f32_32x32x16_bf16 v[16:31], v[144:147], v[186:189], v[16:31]
	v_or_b32_e32 v97, s26, v101
	s_cmp_lt_i32 s4, 22
	v_add_u32_e32 v116, v104, v97
	s_cselect_b64 s[2:3], -1, 0
	s_cmp_gt_i32 s4, 21
	v_add_u32_e32 v112, s0, v103
	s_cselect_b64 s[14:15], -1, 0
	s_add_i32 s27, s26, 0xfffff000
	v_lshlrev_b32_e32 v97, 2, v103
	v_lshlrev_b32_e32 v98, 4, v100
	s_mov_b32 s0, 0x24300
	v_add_u32_e32 v113, 0xfffff000, v116
	v_add3_u32 v120, v97, v98, s0
	v_xor_b32_e32 v97, s27, v113
	s_movk_i32 s4, 0x400
	v_cmp_gt_u32_e64 s[42:43], s4, v97
	s_and_b64 s[4:5], s[14:15], s[42:43]
	v_cndmask_b32_e64 v121, 0, 1, s[2:3]
	s_movk_i32 s2, 0x1000
	v_cndmask_b32_e64 v97, 0, 1, s[4:5]
	v_cmp_gt_i32_e64 s[42:43], s2, v116
	v_ashrrev_i32_e32 v96, 9, v112
	v_cmp_eq_u32_e32 vcc, 4, v96
	v_cndmask_b32_e64 v97, v97, v121, s[42:43]
	v_and_b32_e32 v97, 1, v97
	v_cmp_lt_i32_e64 s[40:41], 2, v96
	v_cmp_lt_u32_e64 s[0:1], 4, v96
	v_cndmask_b32_e32 v96, v178, v179, vcc
	v_cmp_eq_u32_e64 s[44:45], 1, v97
	v_add_u32_e32 v108, v96, v112
	v_subrev_u32_e32 v96, s26, v116
	v_cndmask_b32_e64 v97, v171, 0, s[44:45]
	v_lshl_add_u32 v96, v96, 2, v167
	v_add_u32_e32 v117, v120, v97
	s_barrier
	v_lshlrev_b32_e32 v118, 2, v100
	ds_read_b32 v126, v96
	ds_read_b128 v[96:99], v117
	ds_read_b128 v[100:103], v117 offset:32
	ds_read_b128 v[122:125], v117 offset:64
	v_add_u32_e32 v110, 0xfffff600, v112
	s_movk_i32 s2, 0xfff
	s_waitcnt lgkmcnt(2)
	v_pk_fma_f32 v[104:105], v[80:81], v[126:127], v[96:97] op_sel_hi:[1,0,1]
	v_pk_fma_f32 v[106:107], v[82:83], v[126:127], v[98:99] op_sel_hi:[1,0,1]
	s_waitcnt lgkmcnt(1)
	v_pk_fma_f32 v[100:101], v[84:85], v[126:127], v[100:101] op_sel_hi:[1,0,1]
	ds_read_b128 v[80:83], v117 offset:96
	v_pk_fma_f32 v[102:103], v[86:87], v[126:127], v[102:103] op_sel_hi:[1,0,1]
	ds_read_b128 v[84:87], v117 offset:128
	s_waitcnt lgkmcnt(2)
	v_pk_fma_f32 v[96:97], v[88:89], v[126:127], v[122:123] op_sel_hi:[1,0,1]
	v_pk_fma_f32 v[98:99], v[90:91], v[126:127], v[124:125] op_sel_hi:[1,0,1]
	s_waitcnt lgkmcnt(1)
	v_pk_fma_f32 v[88:89], v[92:93], v[126:127], v[80:81] op_sel_hi:[1,0,1]
	v_pk_fma_f32 v[90:91], v[94:95], v[126:127], v[82:83] op_sel_hi:[1,0,1]
	ds_read_b128 v[80:83], v117 offset:160
	ds_read_b128 v[92:95], v117 offset:192
	s_waitcnt lgkmcnt(2)
	v_pk_fma_f32 v[84:85], v[64:65], v[126:127], v[84:85] op_sel_hi:[1,0,1]
	v_pk_fma_f32 v[86:87], v[66:67], v[126:127], v[86:87] op_sel_hi:[1,0,1]
	ds_read_b128 v[64:67], v117 offset:224
	v_ashrrev_i32_e32 v119, 6, v110
	v_ashrrev_i32_e32 v111, 31, v110
	v_ashrrev_i32_e32 v109, 31, v108
	v_mov_b32_e32 v114, v112
	v_mov_b32_e32 v115, v129
	v_cmp_lt_i32_e64 s[44:45], s2, v116
	s_waitcnt lgkmcnt(2)
	v_pk_fma_f32 v[80:81], v[68:69], v[126:127], v[80:81] op_sel_hi:[1,0,1]
	v_pk_fma_f32 v[82:83], v[70:71], v[126:127], v[82:83] op_sel_hi:[1,0,1]
	s_waitcnt lgkmcnt(1)
	v_pk_fma_f32 v[68:69], v[72:73], v[126:127], v[92:93] op_sel_hi:[1,0,1]
	v_pk_fma_f32 v[70:71], v[74:75], v[126:127], v[94:95] op_sel_hi:[1,0,1]
	s_waitcnt lgkmcnt(0)
	v_pk_fma_f32 v[64:65], v[76:77], v[126:127], v[64:65] op_sel_hi:[1,0,1]
	v_pk_fma_f32 v[66:67], v[78:79], v[126:127], v[66:67] op_sel_hi:[1,0,1]
	s_and_saveexec_b64 s[2:3], s[40:41]
	s_xor_b64 s[2:3], exec, s[2:3]
	s_cbranch_execz .LBB0_880
	s_and_saveexec_b64 s[4:5], s[0:1]
	s_xor_b64 s[4:5], exec, s[4:5]
	s_cbranch_execz .LBB0_859
	v_mov_b64_e32 v[72:73], 0
	s_and_saveexec_b64 s[6:7], s[42:43]
	v_lshrrev_b32_e32 v72, 7, v116
	v_and_b32_e32 v72, 0xfffffe, v72
	v_add_u32_e32 v72, s48, v72
	s_mov_b32 s13, 0x6050400
	v_perm_b32 v72, v72, v116, s13
	v_ashrrev_i32_e32 v73, 31, v72
	v_lshlrev_b64 v[72:73], 11, v[72:73]
	v_lshl_add_u64 v[72:73], s[62:63], 0, v[72:73]
	v_lshl_add_u64 v[72:73], v[110:111], 2, v[72:73]
	s_or_b64 exec, exec, s[6:7]
	s_and_saveexec_b64 s[6:7], s[44:45]
	s_xor_b64 s[6:7], exec, s[6:7]
	v_lshrrev_b32_e32 v74, 7, v113
	v_and_b32_e32 v92, 0x1fffff8, v74
	s_or_saveexec_b64 s[6:7], s[6:7]
	v_mov_b64_e32 v[74:75], 0x400
	v_mov_b32_e32 v75, 0x3ff
	v_mov_b64_e32 v[76:77], 0xdf94000
	v_mov_b64_e32 v[78:79], 17
	s_xor_b64 exec, exec, s[6:7]
	v_ashrrev_i32_e32 v74, 5, v116
	v_and_b32_e32 v92, -8, v74
	v_mov_b64_e32 v[74:75], 0x100
	v_mov_b32_e32 v75, 0xff
	v_mov_b64_e32 v[76:77], 0xdb94000
	v_mov_b64_e32 v[78:79], 15
	s_or_b64 exec, exec, s[6:7]
	v_add_u32_e32 v92, v92, v119
	v_ashrrev_i32_e32 v93, 31, v92
	v_lshl_add_u64 v[76:77], s[50:51], 0, v[76:77]
	v_lshlrev_b64 v[78:79], v78, v[92:93]
	v_and_b32_e32 v75, v75, v116
	v_lshl_add_u64 v[76:77], v[76:77], 0, v[78:79]
	v_lshlrev_b32_e32 v128, 1, v75
	v_mul_u32_u24_e32 v75, v74, v118
	v_lshl_add_u64 v[76:77], v[76:77], 0, v[128:129]
	v_lshlrev_b32_e32 v128, 1, v75
	v_lshl_add_u64 v[78:79], v[76:77], 0, v[128:129]
	v_cvt_pk_bf16_f32 v75, v104, s0
	global_store_short v[78:79], v75, off
	v_or_b32_e32 v75, 1, v118
	v_mul_u32_u24_e32 v75, v74, v75
	v_lshlrev_b32_e32 v128, 1, v75
	v_lshl_add_u64 v[78:79], v[76:77], 0, v[128:129]
	v_cvt_pk_bf16_f32 v75, v105, s0
	global_store_short v[78:79], v75, off
	v_or_b32_e32 v75, 2, v118
	v_mul_u32_u24_e32 v75, v74, v75
	v_lshlrev_b32_e32 v128, 1, v75
	v_lshl_add_u64 v[78:79], v[76:77], 0, v[128:129]
	v_cvt_pk_bf16_f32 v75, v106, s0
	global_store_short v[78:79], v75, off
	v_or_b32_e32 v75, 3, v118
	v_mul_u32_u24_e32 v75, v74, v75
	v_lshlrev_b32_e32 v128, 1, v75
	v_lshl_add_u64 v[78:79], v[76:77], 0, v[128:129]
	v_cvt_pk_bf16_f32 v75, v107, s0
	global_store_short v[78:79], v75, off
	s_and_saveexec_b64 s[6:7], s[42:43]
	s_cbranch_execz .LBB0_844
	v_lshlrev_b32_e32 v128, 2, v118
	v_lshl_add_u64 v[78:79], v[72:73], 0, v[128:129]
	global_store_dwordx4 v[78:79], v[104:107], off

.LBB0_1433:
	s_waitcnt vmcnt(0)
	ds_write_b32 v2, v246
	v_ashrrev_i32_e32 v103, 6, v100
	v_lshrrev_b32_e32 v0, 30, v103
	v_add_u32_e32 v0, v103, v0
	v_ashrrev_i32_e32 v10, 2, v0
	v_mul_i32_i24_e32 v0, 4, v10
	v_ashrrev_i32_e32 v6, 3, v100
	v_sub_u32_e32 v11, v103, v0
	v_lshrrev_b32_e32 v13, 4, v100
	v_add_u32_e32 v0, s4, v6
	v_xor_b32_e32 v7, v13, v100
	v_ashrrev_i32_e32 v1, 31, v0
	v_lshlrev_b64 v[0:1], 13, v[0:1]
	v_lshlrev_b32_e32 v7, 4, v7
	v_lshlrev_b32_e32 v109, 4, v100
	s_and_b32 s8, s2, 0xffffff00
	v_lshl_add_u64 v[4:5], s[52:53], 0, v[0:1]
	v_and_b32_e32 v128, 0x70, v7
	v_readfirstlane_b32 s2, v109
	v_add_u32_e32 v14, 0x2000, v109
	v_lshl_add_u64 v[4:5], v[4:5], 0, v[128:129]
	s_mov_b32 m0, s2
	v_readfirstlane_b32 s2, v14
	ds_write_b32 v2, v3 offset:2048
	v_lshl_add_u64 v[2:3], v[4:5], 0, s[16:17]
	s_mov_b32 m0, s2
	v_add_u32_e32 v6, s8, v6
	v_lshl_add_u64 v[2:3], v[4:5], 0, s[20:21]
	v_add_u32_e32 v4, 0x4000, v109
	v_ashrrev_i32_e32 v7, 31, v6
	v_readfirstlane_b32 s2, v4
	s_mov_b32 m0, s2
	v_lshlrev_b64 v[6:7], 13, v[6:7]
	v_add_u32_e32 v2, 0x6000, v109
	v_lshl_add_u64 v[8:9], s[48:49], 0, v[6:7]
	v_readfirstlane_b32 s2, v2
	v_add_u32_e32 v4, 0x8000, v109
	v_lshl_add_u64 v[8:9], v[8:9], 0, v[128:129]
	s_mov_b32 m0, s2
	v_readfirstlane_b32 s2, v4
	v_add_u32_e32 v4, 0xa000, v109
	v_lshl_add_u64 v[2:3], v[8:9], 0, s[16:17]
	s_mov_b32 m0, s2
	v_readfirstlane_b32 s2, v4
	v_lshl_add_u64 v[2:3], v[8:9], 0, s[20:21]
	s_mov_b32 m0, s2
	s_mov_b64 s[2:3], 0x180000
	v_add_u32_e32 v4, 0xc000, v109
	v_lshl_add_u64 v[2:3], v[8:9], 0, s[2:3]
	v_readfirstlane_b32 s2, v4
	s_mov_b32 m0, s2
	v_and_b32_e32 v102, 31, v100
	v_lshlrev_b32_e32 v105, 6, v11
	v_or_b32_e32 v3, v105, v102
	v_mul_i32_i24_e32 v106, 0x60, v10
	v_bfe_u32 v12, v100, 5, 1
	v_lshrrev_b32_e32 v104, 1, v100
	v_lshlrev_b32_e32 v112, 7, v3
	v_or_b32_e32 v3, v106, v102
	v_bfe_u32 v2, v100, 1, 3
	v_lshlrev_b32_e32 v113, 7, v3
	v_bitop3_b32 v3, v12, v104, 7 bitop3:0x78
	v_lshlrev_b32_e32 v111, 4, v3
	v_bitop3_b32 v3, v12, v2, 2 bitop3:0x36
	v_lshlrev_b32_e32 v110, 4, v3
	v_bitop3_b32 v3, v12, v2, 4 bitop3:0x36
	v_bitop3_b32 v2, v12, v2, 6 bitop3:0x36
	v_lshlrev_b32_e32 v107, 4, v2
	v_bitop3_b32 v2, v13, 7, v100 bitop3:0x48
	v_lshlrev_b32_e32 v2, 4, v2
	v_or_b32_e32 v6, v6, v2
	v_or_b32_e32 v0, v0, v2
	v_and_b32_e32 v101, 63, v100
	v_lshlrev_b32_e32 v108, 4, v3
	v_add_u32_e32 v114, 0x6000, v112
	v_lshl_add_u64 v[96:97], s[60:61], 0, v[6:7]
	v_lshl_add_u64 v[98:99], s[14:15], 0, v[0:1]
	s_mov_b32 s7, 0
	s_mov_b64 s[2:3], 0
	v_mov_b32_e32 v33, v32
	v_mov_b32_e32 v34, v32
	v_mov_b32_e32 v35, v32
	v_mov_b32_e32 v36, v32
	v_mov_b32_e32 v37, v32
	v_mov_b32_e32 v38, v32
	v_mov_b32_e32 v39, v32
	v_mov_b32_e32 v40, v32
	v_mov_b32_e32 v41, v32
	v_mov_b32_e32 v42, v32
	v_mov_b32_e32 v43, v32
	v_mov_b32_e32 v44, v32
	v_mov_b32_e32 v45, v32
	v_mov_b32_e32 v46, v32
	v_mov_b32_e32 v47, v32
	v_mov_b32_e32 v64, v32
	v_mov_b32_e32 v65, v32
	v_mov_b32_e32 v66, v32
	v_mov_b32_e32 v67, v32
	v_mov_b32_e32 v68, v32
	v_mov_b32_e32 v69, v32
	v_mov_b32_e32 v70, v32
	v_mov_b32_e32 v71, v32
	v_mov_b32_e32 v72, v32
	v_mov_b32_e32 v73, v32
	v_mov_b32_e32 v74, v32
	v_mov_b32_e32 v75, v32
	v_mov_b32_e32 v76, v32
	v_mov_b32_e32 v77, v32
	v_mov_b32_e32 v78, v32
	v_mov_b32_e32 v79, v32
	v_mov_b32_e32 v0, v32
	v_mov_b32_e32 v1, v32
	v_mov_b32_e32 v2, v32
	v_mov_b32_e32 v3, v32
	v_mov_b32_e32 v4, v32
	v_mov_b32_e32 v5, v32
	v_mov_b32_e32 v6, v32
	v_mov_b32_e32 v7, v32
	v_mov_b32_e32 v8, v32
	v_mov_b32_e32 v9, v32
	v_mov_b32_e32 v10, v32
	v_mov_b32_e32 v11, v32
	v_mov_b32_e32 v12, v32
	v_mov_b32_e32 v13, v32
	v_mov_b32_e32 v14, v32
	v_mov_b32_e32 v15, v32
	v_mov_b32_e32 v80, v32
	v_mov_b32_e32 v81, v32
	v_mov_b32_e32 v82, v32
	v_mov_b32_e32 v83, v32
	v_mov_b32_e32 v84, v32
	v_mov_b32_e32 v85, v32
	v_mov_b32_e32 v86, v32
	v_mov_b32_e32 v87, v32
	v_mov_b32_e32 v88, v32
	v_mov_b32_e32 v89, v32
	v_mov_b32_e32 v90, v32
	v_mov_b32_e32 v91, v32
	v_mov_b32_e32 v92, v32
	v_mov_b32_e32 v93, v32
	v_mov_b32_e32 v94, v32
	v_mov_b32_e32 v95, v32
	v_mov_b32_e32 v48, v32
	v_mov_b32_e32 v49, v32
	v_mov_b32_e32 v50, v32
	v_mov_b32_e32 v51, v32
	v_mov_b32_e32 v52, v32
	v_mov_b32_e32 v53, v32
	v_mov_b32_e32 v54, v32
	v_mov_b32_e32 v55, v32
	v_mov_b32_e32 v56, v32
	v_mov_b32_e32 v57, v32
	v_mov_b32_e32 v58, v32
	v_mov_b32_e32 v59, v32
	v_mov_b32_e32 v60, v32
	v_mov_b32_e32 v61, v32
	v_mov_b32_e32 v62, v32
	v_mov_b32_e32 v63, v32
	v_mov_b32_e32 v16, v32
	v_mov_b32_e32 v17, v32
	v_mov_b32_e32 v18, v32
	v_mov_b32_e32 v19, v32
	v_mov_b32_e32 v20, v32
	v_mov_b32_e32 v21, v32
	v_mov_b32_e32 v22, v32
	v_mov_b32_e32 v23, v32
	v_mov_b32_e32 v24, v32
	v_mov_b32_e32 v25, v32
	v_mov_b32_e32 v26, v32
	v_mov_b32_e32 v27, v32
	v_mov_b32_e32 v28, v32
	v_mov_b32_e32 v29, v32
	v_mov_b32_e32 v30, v32
	v_mov_b32_e32 v31, v32
	v_add_u32_e32 v243, s4, v106
	v_lshrrev_b32_e32 v244, 4, v101
	v_or_b32_e32 v243, v243, v244
	v_and_b32_e32 v244, 15, v100
	v_add_u32_e32 v245, s8, v105
	v_lshl_or_b32 v244, v244, 2, v245
	v_lshlrev_b32_e32 v243, 12, v243
	v_lshl_add_u32 v243, v244, 2, v243
	global_load_dwordx4 v[198:201], v243, s[40:41]
	v_add_u32_e32 v243, 0x4000, v243
	global_load_dwordx4 v[202:205], v243, s[40:41]
	v_add_u32_e32 v243, 0x4000, v243
	global_load_dwordx4 v[206:209], v243, s[40:41]
	v_add_u32_e32 v243, 0x4000, v243
	global_load_dwordx4 v[210:213], v243, s[40:41]
	v_add_u32_e32 v243, 0x4000, v243
	global_load_dwordx4 v[214:217], v243, s[40:41]
	v_add_u32_e32 v243, 0x4000, v243
	global_load_dwordx4 v[218:221], v243, s[40:41]
	v_add_u32_e32 v243, 0x4000, v243
	global_load_dwordx4 v[222:225], v243, s[40:41]
	v_add_u32_e32 v243, 0x4000, v243
	global_load_dwordx4 v[226:229], v243, s[40:41]
	s_add_i32 s9, s7, 1
	s_bitcmp1_b32 s9, 0
	s_cselect_b32 s10, 0xe000, 0
	v_add_u32_e32 v246, s10, v109
	s_bitcmp1_b32 s7, 0
	s_cselect_b32 s10, 0xe000, 0
	v_add_u32_e32 v153, s10, v114
	v_add_u32_e32 v154, s10, v113
	s_waitcnt vmcnt(0) lgkmcnt(0)
	s_barrier
	v_add_u32_e32 v181, v153, v111
	ds_read_b128 v[116:119], v181 offset:0x0
	ds_read_b128 v[120:123], v181 offset:0x1000
	v_add_u32_e32 v181, v154, v111
	ds_read_b128 v[124:127], v181 offset:0x0
	ds_read_b128 v[130:133], v181 offset:0x1000
	ds_read_b128 v[134:137], v181 offset:0x2000
	v_add_u32_e32 v181, v153, v110
	ds_read_b128 v[144:147], v181 offset:0x0
	ds_read_b128 v[148:151], v181 offset:0x1000
	v_add_u32_e32 v181, v154, v110
	ds_read_b128 v[182:185], v181 offset:0x0
	ds_read_b128 v[186:189], v181 offset:0x1000
	ds_read_b128 v[190:193], v181 offset:0x2000
	s_waitcnt lgkmcnt(5)
	v_mfma_f32_32x32x16_bf16 v[64:79], v[116:119], v[124:127], v[64:79]
	v_mfma_f32_32x32x16_bf16 v[32:47], v[116:119], v[130:133], v[32:47]
	s_mov_b64 s[10:11], 0x9f94080
	v_lshl_add_u64 v[244:245], v[98:99], 0, s[2:3]
	v_lshl_add_u64 v[244:245], v[244:245], 0, s[10:11]
	v_readfirstlane_b32 s10, v246
	s_mov_b32 m0, s10
	s_nop 0
	global_load_lds_dwordx4 v[244:245], off
	v_mfma_f32_32x32x16_bf16 v[0:15], v[116:119], v[134:137], v[0:15]
	v_mfma_f32_32x32x16_bf16 v[80:95], v[120:123], v[124:127], v[80:95]
	v_add_u32_e32 v243, 0x2000, v246
	s_mov_b64 s[10:11], 0xa014080
	v_lshl_add_u64 v[244:245], v[98:99], 0, s[2:3]
	v_lshl_add_u64 v[244:245], v[244:245], 0, s[10:11]
	v_readfirstlane_b32 s10, v243
	s_mov_b32 m0, s10
	s_nop 0
	global_load_lds_dwordx4 v[244:245], off
	v_mfma_f32_32x32x16_bf16 v[48:63], v[120:123], v[130:133], v[48:63]
	v_mfma_f32_32x32x16_bf16 v[16:31], v[120:123], v[134:137], v[16:31]
	v_add_u32_e32 v243, 0x4000, v246
	s_mov_b64 s[10:11], 0xa094080
	v_lshl_add_u64 v[244:245], v[98:99], 0, s[2:3]
	v_lshl_add_u64 v[244:245], v[244:245], 0, s[10:11]
	v_readfirstlane_b32 s10, v243
	s_mov_b32 m0, s10
	s_nop 0
	global_load_lds_dwordx4 v[244:245], off
	v_add_u32_e32 v181, v153, v108
	ds_read_b128 v[116:119], v181 offset:0x0
	ds_read_b128 v[120:123], v181 offset:0x1000
	v_add_u32_e32 v181, v154, v108
	ds_read_b128 v[124:127], v181 offset:0x0
	ds_read_b128 v[130:133], v181 offset:0x1000
	ds_read_b128 v[134:137], v181 offset:0x2000
	s_waitcnt lgkmcnt(5)
	v_mfma_f32_32x32x16_bf16 v[64:79], v[144:147], v[182:185], v[64:79]
	v_mfma_f32_32x32x16_bf16 v[32:47], v[144:147], v[186:189], v[32:47]
	v_add_u32_e32 v243, 0x6000, v246
	s_mov_b64 s[10:11], 0x3314080
	v_lshl_add_u64 v[244:245], v[96:97], 0, s[2:3]
	v_lshl_add_u64 v[244:245], v[244:245], 0, s[10:11]
	v_readfirstlane_b32 s10, v243
	s_mov_b32 m0, s10
	s_nop 0
	global_load_lds_dwordx4 v[244:245], off
	v_mfma_f32_32x32x16_bf16 v[0:15], v[144:147], v[190:193], v[0:15]
	v_mfma_f32_32x32x16_bf16 v[80:95], v[148:151], v[182:185], v[80:95]
	v_add_u32_e32 v243, 0x8000, v246
	s_mov_b64 s[10:11], 0x3394080
	v_lshl_add_u64 v[244:245], v[96:97], 0, s[2:3]
	v_lshl_add_u64 v[244:245], v[244:245], 0, s[10:11]
	v_readfirstlane_b32 s10, v243
	s_mov_b32 m0, s10
	s_nop 0
	global_load_lds_dwordx4 v[244:245], off
	v_mfma_f32_32x32x16_bf16 v[48:63], v[148:151], v[186:189], v[48:63]
	v_mfma_f32_32x32x16_bf16 v[16:31], v[148:151], v[190:193], v[16:31]
	v_add_u32_e32 v243, 0xa000, v246
	s_mov_b64 s[10:11], 0x3414080
	v_lshl_add_u64 v[244:245], v[96:97], 0, s[2:3]
	v_lshl_add_u64 v[244:245], v[244:245], 0, s[10:11]
	v_readfirstlane_b32 s10, v243
	s_mov_b32 m0, s10
	s_nop 0
	global_load_lds_dwordx4 v[244:245], off
	v_add_u32_e32 v181, v153, v107
	ds_read_b128 v[144:147], v181 offset:0x0
	ds_read_b128 v[148:151], v181 offset:0x1000
	v_add_u32_e32 v181, v154, v107
	ds_read_b128 v[182:185], v181 offset:0x0
	ds_read_b128 v[186:189], v181 offset:0x1000
	ds_read_b128 v[190:193], v181 offset:0x2000
	s_waitcnt lgkmcnt(5)
	v_mfma_f32_32x32x16_bf16 v[64:79], v[116:119], v[124:127], v[64:79]
	v_mfma_f32_32x32x16_bf16 v[32:47], v[116:119], v[130:133], v[32:47]
	v_add_u32_e32 v243, 0xc000, v246
	s_mov_b64 s[10:11], 0x3494080
	v_lshl_add_u64 v[244:245], v[96:97], 0, s[2:3]
	v_lshl_add_u64 v[244:245], v[244:245], 0, s[10:11]
	v_readfirstlane_b32 s10, v243
	s_mov_b32 m0, s10
	s_nop 0
	global_load_lds_dwordx4 v[244:245], off
	v_mfma_f32_32x32x16_bf16 v[0:15], v[116:119], v[134:137], v[0:15]
	v_mfma_f32_32x32x16_bf16 v[80:95], v[120:123], v[124:127], v[80:95]
	v_mfma_f32_32x32x16_bf16 v[48:63], v[120:123], v[130:133], v[48:63]
	v_mfma_f32_32x32x16_bf16 v[16:31], v[120:123], v[134:137], v[16:31]
	s_waitcnt lgkmcnt(0)
	s_add_u32 s2, s2, 0x80
	s_addc_u32 s3, s3, 0
	s_mov_b32 s7, s9
.LBB0_1434:
	s_add_i32 s9, s7, 1
	s_bitcmp1_b32 s9, 0
	s_cselect_b32 s10, 0xe000, 0
	v_add_u32_e32 v246, s10, v109
	s_bitcmp1_b32 s7, 0
	s_cselect_b32 s10, 0xe000, 0
	v_add_u32_e32 v153, s10, v114
	v_add_u32_e32 v154, s10, v113
	s_waitcnt vmcnt(0) lgkmcnt(0)
	s_barrier
	v_add_u32_e32 v181, v153, v111
	ds_read_b128 v[116:119], v181 offset:0x0
	ds_read_b128 v[120:123], v181 offset:0x1000
	v_add_u32_e32 v181, v154, v111
	ds_read_b128 v[124:127], v181 offset:0x0
	ds_read_b128 v[130:133], v181 offset:0x1000
	ds_read_b128 v[134:137], v181 offset:0x2000
	v_mfma_f32_32x32x16_bf16 v[64:79], v[144:147], v[182:185], v[64:79]
	v_mfma_f32_32x32x16_bf16 v[32:47], v[144:147], v[186:189], v[32:47]
	s_mov_b64 s[10:11], 0x9f94080
	v_lshl_add_u64 v[244:245], v[98:99], 0, s[2:3]
	v_lshl_add_u64 v[244:245], v[244:245], 0, s[10:11]
	v_readfirstlane_b32 s10, v246
	s_mov_b32 m0, s10
	s_nop 0
	global_load_lds_dwordx4 v[244:245], off
	v_mfma_f32_32x32x16_bf16 v[0:15], v[144:147], v[190:193], v[0:15]
	v_mfma_f32_32x32x16_bf16 v[80:95], v[148:151], v[182:185], v[80:95]
	v_add_u32_e32 v243, 0x2000, v246
	s_mov_b64 s[10:11], 0xa014080
	v_lshl_add_u64 v[244:245], v[98:99], 0, s[2:3]
	v_lshl_add_u64 v[244:245], v[244:245], 0, s[10:11]
	v_readfirstlane_b32 s10, v243
	s_mov_b32 m0, s10
	s_nop 0
	global_load_lds_dwordx4 v[244:245], off
	v_mfma_f32_32x32x16_bf16 v[48:63], v[148:151], v[186:189], v[48:63]
	v_mfma_f32_32x32x16_bf16 v[16:31], v[148:151], v[190:193], v[16:31]
	v_add_u32_e32 v243, 0x4000, v246
	s_mov_b64 s[10:11], 0xa094080
	v_lshl_add_u64 v[244:245], v[98:99], 0, s[2:3]
	v_lshl_add_u64 v[244:245], v[244:245], 0, s[10:11]
	v_readfirstlane_b32 s10, v243
	s_mov_b32 m0, s10
	s_nop 0
	global_load_lds_dwordx4 v[244:245], off
	v_add_u32_e32 v181, v153, v110
	ds_read_b128 v[144:147], v181 offset:0x0
	ds_read_b128 v[148:151], v181 offset:0x1000
	v_add_u32_e32 v181, v154, v110
	ds_read_b128 v[182:185], v181 offset:0x0
	ds_read_b128 v[186:189], v181 offset:0x1000
	ds_read_b128 v[190:193], v181 offset:0x2000
	s_waitcnt lgkmcnt(5)
	v_mfma_f32_32x32x16_bf16 v[64:79], v[116:119], v[124:127], v[64:79]
	v_mfma_f32_32x32x16_bf16 v[32:47], v[116:119], v[130:133], v[32:47]
	v_add_u32_e32 v243, 0x6000, v246
	s_mov_b64 s[10:11], 0x3314080
	v_lshl_add_u64 v[244:245], v[96:97], 0, s[2:3]
	v_lshl_add_u64 v[244:245], v[244:245], 0, s[10:11]
	v_readfirstlane_b32 s10, v243
	s_mov_b32 m0, s10
	s_nop 0
	global_load_lds_dwordx4 v[244:245], off
	v_mfma_f32_32x32x16_bf16 v[0:15], v[116:119], v[134:137], v[0:15]
	v_mfma_f32_32x32x16_bf16 v[80:95], v[120:123], v[124:127], v[80:95]
	v_add_u32_e32 v243, 0x8000, v246
	s_mov_b64 s[10:11], 0x3394080
	v_lshl_add_u64 v[244:245], v[96:97], 0, s[2:3]
	v_lshl_add_u64 v[244:245], v[244:245], 0, s[10:11]
	v_readfirstlane_b32 s10, v243
	s_mov_b32 m0, s10
	s_nop 0
	global_load_lds_dwordx4 v[244:245], off
	v_mfma_f32_32x32x16_bf16 v[48:63], v[120:123], v[130:133], v[48:63]
	v_mfma_f32_32x32x16_bf16 v[16:31], v[120:123], v[134:137], v[16:31]
	v_add_u32_e32 v243, 0xa000, v246
	s_mov_b64 s[10:11], 0x3414080
	v_lshl_add_u64 v[244:245], v[96:97], 0, s[2:3]
	v_lshl_add_u64 v[244:245], v[244:245], 0, s[10:11]
	v_readfirstlane_b32 s10, v243
	s_mov_b32 m0, s10
	s_nop 0
	global_load_lds_dwordx4 v[244:245], off
	v_add_u32_e32 v181, v153, v108
	ds_read_b128 v[116:119], v181 offset:0x0
	ds_read_b128 v[120:123], v181 offset:0x1000
	v_add_u32_e32 v181, v154, v108
	ds_read_b128 v[124:127], v181 offset:0x0
	ds_read_b128 v[130:133], v181 offset:0x1000
	ds_read_b128 v[134:137], v181 offset:0x2000
	s_waitcnt lgkmcnt(5)
	v_mfma_f32_32x32x16_bf16 v[64:79], v[144:147], v[182:185], v[64:79]
	v_mfma_f32_32x32x16_bf16 v[32:47], v[144:147], v[186:189], v[32:47]
	v_add_u32_e32 v243, 0xc000, v246
	s_mov_b64 s[10:11], 0x3494080
	v_lshl_add_u64 v[244:245], v[96:97], 0, s[2:3]
	v_lshl_add_u64 v[244:245], v[244:245], 0, s[10:11]
	v_readfirstlane_b32 s10, v243
	s_mov_b32 m0, s10
	s_nop 0
	global_load_lds_dwordx4 v[244:245], off
	v_mfma_f32_32x32x16_bf16 v[0:15], v[144:147], v[190:193], v[0:15]
	v_mfma_f32_32x32x16_bf16 v[80:95], v[148:151], v[182:185], v[80:95]
	v_mfma_f32_32x32x16_bf16 v[48:63], v[148:151], v[186:189], v[48:63]
	v_mfma_f32_32x32x16_bf16 v[16:31], v[148:151], v[190:193], v[16:31]
	v_add_u32_e32 v181, v153, v107
	ds_read_b128 v[144:147], v181 offset:0x0
	ds_read_b128 v[148:151], v181 offset:0x1000
	v_add_u32_e32 v181, v154, v107
	ds_read_b128 v[182:185], v181 offset:0x0
	ds_read_b128 v[186:189], v181 offset:0x1000
	ds_read_b128 v[190:193], v181 offset:0x2000
	s_waitcnt lgkmcnt(5)
	v_mfma_f32_32x32x16_bf16 v[64:79], v[116:119], v[124:127], v[64:79]
	v_mfma_f32_32x32x16_bf16 v[32:47], v[116:119], v[130:133], v[32:47]
	v_mfma_f32_32x32x16_bf16 v[0:15], v[116:119], v[134:137], v[0:15]
	v_mfma_f32_32x32x16_bf16 v[80:95], v[120:123], v[124:127], v[80:95]
	v_mfma_f32_32x32x16_bf16 v[48:63], v[120:123], v[130:133], v[48:63]
	v_mfma_f32_32x32x16_bf16 v[16:31], v[120:123], v[134:137], v[16:31]
	s_waitcnt lgkmcnt(0)
	s_add_u32 s2, s2, 0x80
	s_addc_u32 s3, s3, 0
	s_mov_b32 s7, s9
	s_cmpk_lg_i32 s2, 0x1f80
	s_cbranch_scc1 .LBB0_1434
	s_bitcmp1_b32 s7, 0
	s_cselect_b32 s10, 0xe000, 0
	v_add_u32_e32 v153, s10, v114
	v_add_u32_e32 v154, s10, v113
	s_waitcnt vmcnt(0) lgkmcnt(0)
	s_barrier
	v_add_u32_e32 v181, v153, v111
	ds_read_b128 v[116:119], v181 offset:0x0
	ds_read_b128 v[120:123], v181 offset:0x1000
	v_add_u32_e32 v181, v154, v111
	ds_read_b128 v[124:127], v181 offset:0x0
	ds_read_b128 v[130:133], v181 offset:0x1000
	ds_read_b128 v[134:137], v181 offset:0x2000
	v_mfma_f32_32x32x16_bf16 v[64:79], v[144:147], v[182:185], v[64:79]
	v_mfma_f32_32x32x16_bf16 v[32:47], v[144:147], v[186:189], v[32:47]
	v_mfma_f32_32x32x16_bf16 v[0:15], v[144:147], v[190:193], v[0:15]
	v_mfma_f32_32x32x16_bf16 v[80:95], v[148:151], v[182:185], v[80:95]
	v_mfma_f32_32x32x16_bf16 v[48:63], v[148:151], v[186:189], v[48:63]
	v_mfma_f32_32x32x16_bf16 v[16:31], v[148:151], v[190:193], v[16:31]
	v_add_u32_e32 v181, v153, v110
	ds_read_b128 v[144:147], v181 offset:0x0
	ds_read_b128 v[148:151], v181 offset:0x1000
	v_add_u32_e32 v181, v154, v110
	ds_read_b128 v[182:185], v181 offset:0x0
	ds_read_b128 v[186:189], v181 offset:0x1000
	ds_read_b128 v[190:193], v181 offset:0x2000
	s_waitcnt lgkmcnt(5)
	v_mfma_f32_32x32x16_bf16 v[64:79], v[116:119], v[124:127], v[64:79]
	v_mfma_f32_32x32x16_bf16 v[32:47], v[116:119], v[130:133], v[32:47]
	v_mfma_f32_32x32x16_bf16 v[0:15], v[116:119], v[134:137], v[0:15]
	v_mfma_f32_32x32x16_bf16 v[80:95], v[120:123], v[124:127], v[80:95]
	v_mfma_f32_32x32x16_bf16 v[48:63], v[120:123], v[130:133], v[48:63]
	v_mfma_f32_32x32x16_bf16 v[16:31], v[120:123], v[134:137], v[16:31]
	v_add_u32_e32 v181, v153, v108
	ds_read_b128 v[116:119], v181 offset:0x0
	ds_read_b128 v[120:123], v181 offset:0x1000
	v_add_u32_e32 v181, v154, v108
	ds_read_b128 v[124:127], v181 offset:0x0
	ds_read_b128 v[130:133], v181 offset:0x1000
	ds_read_b128 v[134:137], v181 offset:0x2000
	s_waitcnt lgkmcnt(5)
	v_mfma_f32_32x32x16_bf16 v[64:79], v[144:147], v[182:185], v[64:79]
	v_mfma_f32_32x32x16_bf16 v[32:47], v[144:147], v[186:189], v[32:47]
	v_mfma_f32_32x32x16_bf16 v[0:15], v[144:147], v[190:193], v[0:15]
	v_mfma_f32_32x32x16_bf16 v[80:95], v[148:151], v[182:185], v[80:95]
	v_mfma_f32_32x32x16_bf16 v[48:63], v[148:151], v[186:189], v[48:63]
	v_mfma_f32_32x32x16_bf16 v[16:31], v[148:151], v[190:193], v[16:31]
	v_add_u32_e32 v181, v153, v107
	ds_read_b128 v[144:147], v181 offset:0x0
	ds_read_b128 v[148:151], v181 offset:0x1000
	v_add_u32_e32 v181, v154, v107
	ds_read_b128 v[182:185], v181 offset:0x0
	ds_read_b128 v[186:189], v181 offset:0x1000
	ds_read_b128 v[190:193], v181 offset:0x2000
	s_waitcnt lgkmcnt(5)
	v_mfma_f32_32x32x16_bf16 v[64:79], v[116:119], v[124:127], v[64:79]
	v_mfma_f32_32x32x16_bf16 v[32:47], v[116:119], v[130:133], v[32:47]
	v_mfma_f32_32x32x16_bf16 v[0:15], v[116:119], v[134:137], v[0:15]
	v_mfma_f32_32x32x16_bf16 v[80:95], v[120:123], v[124:127], v[80:95]
	v_mfma_f32_32x32x16_bf16 v[48:63], v[120:123], v[130:133], v[48:63]
	v_mfma_f32_32x32x16_bf16 v[16:31], v[120:123], v[134:137], v[16:31]
	s_waitcnt lgkmcnt(0)
	v_mfma_f32_32x32x16_bf16 v[64:79], v[144:147], v[182:185], v[64:79]
	v_mfma_f32_32x32x16_bf16 v[32:47], v[144:147], v[186:189], v[32:47]
	v_mfma_f32_32x32x16_bf16 v[0:15], v[144:147], v[190:193], v[0:15]
	v_mfma_f32_32x32x16_bf16 v[80:95], v[148:151], v[182:185], v[80:95]
	v_mfma_f32_32x32x16_bf16 v[48:63], v[148:151], v[186:189], v[48:63]
	v_mfma_f32_32x32x16_bf16 v[16:31], v[148:151], v[190:193], v[16:31]
	v_add_u32_e32 v96, s4, v106
	v_lshrrev_b32_e32 v128, 4, v101
	v_and_b32_e32 v112, 15, v100
	v_or_b32_e32 v100, v96, v128
	v_add_u32_e32 v105, s8, v105
	v_ashrrev_i32_e32 v101, 31, v100
	v_lshl_or_b32 v98, v112, 2, v105
	v_lshlrev_b64 v[106:107], 12, v[100:101]
	v_ashrrev_i32_e32 v99, 31, v98
	v_lshl_add_u64 v[106:107], s[40:41], 0, v[106:107]
	v_lshl_add_u64 v[110:111], v[98:99], 2, v[106:107]
	s_barrier
	v_add_co_u32_e32 v182, vcc, 0x20000, v110
	s_nop 1
	v_addc_co_u32_e32 v183, vcc, 0, v111, vcc
	global_load_dwordx4 v[184:187], v[182:183], off
	v_add_co_u32_e32 v182, vcc, 0x4000, v182
	s_nop 1
	v_addc_co_u32_e32 v183, vcc, 0, v183, vcc
	global_load_dwordx4 v[188:191], v[182:183], off
	v_add_co_u32_e32 v182, vcc, 0x4000, v182
	s_nop 1
	v_addc_co_u32_e32 v183, vcc, 0, v183, vcc
	global_load_dwordx4 v[192:195], v[182:183], off
	v_add_co_u32_e32 v182, vcc, 0x4000, v182
	s_nop 1
	v_addc_co_u32_e32 v183, vcc, 0, v183, vcc
	global_load_dwordx4 v[116:119], v[182:183], off
	v_add_co_u32_e32 v182, vcc, 0x4000, v182
	s_nop 1
	v_addc_co_u32_e32 v183, vcc, 0, v183, vcc
	global_load_dwordx4 v[120:123], v[182:183], off
	v_add_co_u32_e32 v182, vcc, 0x4000, v182
	s_nop 1
	v_addc_co_u32_e32 v183, vcc, 0, v183, vcc
	global_load_dwordx4 v[124:127], v[182:183], off
	v_add_co_u32_e32 v182, vcc, 0x4000, v182
	s_nop 1
	v_addc_co_u32_e32 v183, vcc, 0, v183, vcc
	global_load_dwordx4 v[130:133], v[182:183], off
	v_add_co_u32_e32 v182, vcc, 0x4000, v182
	s_nop 1
	v_addc_co_u32_e32 v183, vcc, 0, v183, vcc
	global_load_dwordx4 v[134:137], v[182:183], off
	s_movk_i32 s2, 0x2400
	s_cmp_lt_i32 s5, 22
	v_mul_lo_u32 v97, v103, s2
	s_cselect_b64 s[2:3], -1, 0
	s_cmp_gt_i32 s5, 21
	s_movk_i32 s5, 0x110
	v_and_b32_e32 v103, 16, v104
	v_mad_u32_u24 v104, v102, s5, v97
	v_add_u32_e32 v113, 0xfffff000, v96
	v_cndmask_b32_e64 v102, 0, 1, s[2:3]
	s_cselect_b64 s[2:3], -1, 0
	s_add_i32 s7, s4, 0xfffff000
	v_add_u32_e32 v104, v104, v103
	ds_write_b128 v104, v[64:67]
	ds_write_b128 v104, v[68:71] offset:32
	ds_write_b128 v104, v[72:75] offset:64
	ds_write_b128 v104, v[76:79] offset:96
	ds_write_b128 v104, v[80:83] offset:128
	ds_write_b128 v104, v[84:87] offset:160
	ds_write_b128 v104, v[88:91] offset:192
	ds_write_b128 v104, v[92:95] offset:224
	v_xor_b32_e32 v64, s7, v113
	s_movk_i32 s4, 0x400
	v_lshl_or_b32 v97, v112, 4, v97
	v_cmp_gt_u32_e32 vcc, s4, v64
	v_mad_u32_u24 v115, v128, s5, v97
	s_and_b64 s[4:5], s[2:3], vcc
	v_cndmask_b32_e64 v71, 0, 1, s[4:5]
	s_movk_i32 s4, 0x1000
	v_cmp_gt_i32_e32 vcc, s4, v100
	v_subrev_u32_e32 v114, s8, v98
	v_lshl_add_u32 v103, v114, 2, v167
	v_cndmask_b32_e32 v64, v71, v102, vcc
	v_and_b32_e32 v64, 1, v64
	v_cmp_eq_u32_e32 vcc, 1, v64
	v_ashrrev_i32_e32 v68, 6, v105
	s_mov_b32 s4, 0xc000
	v_cndmask_b32_e64 v64, v171, 0, vcc
	v_add_u32_e32 v70, v103, v64
	ds_read_b128 v[64:67], v115
	ds_read_b128 v[72:75], v70
	v_cmp_eq_u32_e64 s[36:37], 0, v112
	v_mad_i64_i32 v[68:69], s[4:5], v68, s4, 0
	s_and_b64 vcc, exec, s[0:1]
	s_waitcnt lgkmcnt(0)
	v_pk_fma_f32 v[66:67], v[66:67], v[74:75], v[200:201]
	v_pk_fma_f32 v[64:65], v[64:65], v[72:73], v[198:199]
	global_store_dwordx4 v[110:111], v[64:67], off
	s_cbranch_vccnz .LBB0_1439
	ds_read_b128 v[72:75], v70 offset:2048
	v_lshlrev_b64 v[76:77], 10, v[100:101]
	v_lshl_add_u64 v[76:77], v[76:77], 1, s[50:51]
	v_lshl_add_u64 v[76:77], v[98:99], 1, v[76:77]
	s_waitcnt lgkmcnt(0)
	v_pk_mul_f32 v[72:73], v[64:65], v[72:73]
	v_pk_mul_f32 v[64:65], v[64:65], v[64:65]
	v_pk_mul_f32 v[74:75], v[66:67], v[74:75]
	v_pk_mul_f32 v[66:67], v[66:67], v[66:67]
	v_add_f32_e32 v64, v64, v65
	v_add_f32_e32 v64, v66, v64
	v_add_f32_e32 v64, v67, v64
	v_cvt_pk_bf16_f32 v72, v72, v73
	v_cvt_pk_bf16_f32 v73, v74, v75
	v_add_f32_dpp v64, v64, v64 quad_perm:[1,0,3,2] row_mask:0xf bank_mask:0xf bound_ctrl:1
	global_store_dwordx2 v[76:77], v[72:73], off
	s_nop 0
	v_add_f32_dpp v64, v64, v64 quad_perm:[2,3,0,1] row_mask:0xf bank_mask:0xf bound_ctrl:1
	s_nop 1
	v_add_f32_dpp v64, v64, v64 row_half_mirror row_mask:0xf bank_mask:0xf bound_ctrl:1
	s_nop 1
	v_mov_b32_dpp v65, v64 row_mirror row_mask:0xf bank_mask:0xf bound_ctrl:1
	s_and_saveexec_b64 s[4:5], s[36:37]
	s_cbranch_execz .LBB0_1438
	v_lshl_add_u64 v[66:67], s[54:55], 0, v[68:69]
	v_lshl_add_u64 v[66:67], v[100:101], 2, v[66:67]
	v_add_f32_e32 v64, v64, v65
	global_store_dword v[66:67], v64, off
